# GEMM K-loops: s_setprio 1 moved before the pre-MFMA barrier, redundant post-barrier lgkmcnt(0) dropped, s_setprio 0 moved after the closing barrier (24+24 sites, v010 base)
# speedup vs baseline: 1.0039x; 1.0039x over previous
; #define PG8_STAGE(bufoff, gbase, voff) do { _Pragma("unroll") for (int _i = 0; _i < 2; ++_i) \
;         __builtin_amdgcn_global_load_lds((const unsigned*)((const char*)(gbase) + (voff)[_i]), (PG8_LAS unsigned*)(lds + (bufoff) + ldsw + _i * 8192), 16, 0, 0); } while (0)
; #define PG8_LDA(dst, b, h) do { _Pragma("unroll") for (int m = 0; m < 4; ++m) _Pragma("unroll") for (int k = 0; k < 2; ++k) dst[m][k] = *(const PG8_LAS bf16x8*)(lds + PG8_SA(b, h) + aoff + m * 2048 + k * 1024); } while (0)
; #define PG8_LDB(dst, b, h) do { _Pragma("unroll") for (int n = 0; n < 2; ++n) _Pragma("unroll") for (int k = 0; k < 2; ++k) dst[n][k] = *(const PG8_LAS bf16x8*)(lds + PG8_SB(b, h) + boff + n * 2048 + k * 1024); } while (0)
; #define PG8_MMA(ai, bj, At, Bt) do { __builtin_amdgcn_s_setprio(1); _Pragma("unroll") for (int m = 0; m < 4; ++m) _Pragma("unroll") for (int n = 0; n < 2; ++n) _Pragma("unroll") for (int k = 0; k < 2; ++k) \
;         acc[ai][bj][m][n] = __builtin_amdgcn_mfma_f32_16x16x32_bf16(Bt[n][k], At[m][k], acc[ai][bj][m][n], 0, 0, 0); __builtin_amdgcn_s_setprio(0); } while (0)
; #define PG8_WAIT_V(n) asm volatile("s_waitcnt vmcnt(" #n ")" ::: "memory")
; #define PG8_WAIT_L(n) asm volatile("s_waitcnt lgkmcnt(" #n ")" ::: "memory")
; #define PG8_BAR __builtin_amdgcn_s_barrier()
; #define PG8_SCHED __builtin_amdgcn_sched_barrier(0)
; template <class Epi, class Sched, bool ALIGN_EPI = false, bool SP2 = false>
; __device__ __forceinline__ void gemm_phase(PG8_LAS unsigned char* lds, const Gemm g, const Sched& S, const Epi& E) {
;     ...
;             PG8_LDB(B0, 0, 0); PG8_LDB(B1, 0, 1); PG8_SCHED; PG8_LDA(At, 0, 0); PG8_STAGE(PG8_SA(1, 1), a1 + hstepA, voffA);
;             PG8_WAIT_V(8); PG8_WAIT_L(0); PG8_BAR; PG8_MMA(0, 0, At, B0); PG8_MMA(0, 1, At, B1); PG8_BAR; PG8_SCHED;
;             PG8_LDA(At, 0, 1); PG8_STAGE(PG8_SB(0, 0), b2, voffB); PG8_STAGE(PG8_SB(0, 1), b2 + hstepB, voffB); PG8_STAGE(PG8_SA(0, 0), a2, voffA);
;             PG8_WAIT_V(8); PG8_WAIT_L(0); PG8_BAR; PG8_MMA(1, 0, At, B0); PG8_MMA(1, 1, At, B1); PG8_BAR; PG8_SCHED;
.LBB0_177:
	ds_read_b128 v[128:131], v183
	ds_read_b128 v[132:135], v183 offset:1024
	ds_read_b128 v[136:139], v183 offset:2048
	ds_read_b128 v[140:143], v183 offset:3072
	ds_read_b128 v[166:169], v184
	ds_read_b128 v[170:173], v184 offset:1024
	ds_read_b128 v[188:191], v184 offset:2048
	ds_read_b128 v[196:199], v184 offset:3072
	s_add_u32 s12, s10, 0xfff80080
	s_addc_u32 s13, s11, -1
	s_cmp_eq_u32 s55, 28
	s_cselect_b32 s59, s0, s13
	s_cselect_b32 s58, s2, s12
	s_cselect_b32 s13, s3, s33
	s_cselect_b32 s12, s7, s9
	v_lshl_add_u64 v[192:193], s[10:11], 0, v[158:159]
	s_add_i32 m0, s74, 0xc000
	ds_read_b128 v[200:203], v185
	ds_read_b128 v[204:207], v185 offset:1024
	ds_read_b128 v[208:211], v185 offset:2048
	ds_read_b128 v[212:215], v185 offset:3072
	ds_read_b128 v[216:219], v185 offset:4096
	ds_read_b128 v[220:223], v185 offset:5120
	ds_read_b128 v[224:227], v185 offset:6144
	ds_read_b128 v[228:231], v185 offset:7168
	global_load_lds_dwordx4 v[192:193], off
	v_lshl_add_u64 v[192:193], s[10:11], 0, v[160:161]
	s_add_i32 m0, s74, 0xe000
	s_nop 0
	global_load_lds_dwordx4 v[192:193], off
	s_waitcnt vmcnt(8)
	s_waitcnt lgkmcnt(0)
	s_setprio 1
	s_barrier
	v_mfma_f32_16x16x32_bf16 v[124:127], v[128:131], v[200:203], v[124:127]
	v_mfma_f32_16x16x32_bf16 v[120:123], v[136:139], v[200:203], v[120:123]
	v_mfma_f32_16x16x32_bf16 v[116:119], v[128:131], v[208:211], v[116:119]
	v_mfma_f32_16x16x32_bf16 v[112:115], v[136:139], v[208:211], v[112:115]
	v_mfma_f32_16x16x32_bf16 v[100:103], v[128:131], v[216:219], v[100:103]
	v_mfma_f32_16x16x32_bf16 v[96:99], v[136:139], v[216:219], v[96:99]
	v_mfma_f32_16x16x32_bf16 v[84:87], v[128:131], v[224:227], v[84:87]
	v_mfma_f32_16x16x32_bf16 v[80:83], v[136:139], v[224:227], v[80:83]
	v_mfma_f32_16x16x32_bf16 v[124:127], v[132:135], v[204:207], v[124:127]
	v_mfma_f32_16x16x32_bf16 v[120:123], v[140:143], v[204:207], v[120:123]
	v_mfma_f32_16x16x32_bf16 v[116:119], v[132:135], v[212:215], v[116:119]
	v_mfma_f32_16x16x32_bf16 v[112:115], v[140:143], v[212:215], v[112:115]
	v_mfma_f32_16x16x32_bf16 v[100:103], v[132:135], v[220:223], v[100:103]
	v_mfma_f32_16x16x32_bf16 v[96:99], v[140:143], v[220:223], v[96:99]
	v_mfma_f32_16x16x32_bf16 v[84:87], v[132:135], v[228:231], v[84:87]
	v_mfma_f32_16x16x32_bf16 v[80:83], v[140:143], v[228:231], v[80:83]
	s_setprio 0
	s_setprio 1
	v_mfma_f32_16x16x32_bf16 v[108:111], v[166:169], v[200:203], v[108:111]
	v_mfma_f32_16x16x32_bf16 v[104:107], v[188:191], v[200:203], v[104:107]
	v_mfma_f32_16x16x32_bf16 v[92:95], v[166:169], v[208:211], v[92:95]
	v_mfma_f32_16x16x32_bf16 v[88:91], v[188:191], v[208:211], v[88:91]
	v_mfma_f32_16x16x32_bf16 v[76:79], v[166:169], v[216:219], v[76:79]
	v_mfma_f32_16x16x32_bf16 v[72:75], v[188:191], v[216:219], v[72:75]
	v_mfma_f32_16x16x32_bf16 v[68:71], v[166:169], v[224:227], v[68:71]
	v_mfma_f32_16x16x32_bf16 v[64:67], v[188:191], v[224:227], v[64:67]
	v_mfma_f32_16x16x32_bf16 v[108:111], v[170:173], v[204:207], v[108:111]
	v_mfma_f32_16x16x32_bf16 v[104:107], v[196:199], v[204:207], v[104:107]
	v_mfma_f32_16x16x32_bf16 v[92:95], v[170:173], v[212:215], v[92:95]
	v_mfma_f32_16x16x32_bf16 v[88:91], v[196:199], v[212:215], v[88:91]
	v_mfma_f32_16x16x32_bf16 v[76:79], v[170:173], v[220:223], v[76:79]
	v_mfma_f32_16x16x32_bf16 v[72:75], v[196:199], v[220:223], v[72:75]
	v_mfma_f32_16x16x32_bf16 v[68:71], v[170:173], v[228:231], v[68:71]
	v_mfma_f32_16x16x32_bf16 v[64:67], v[196:199], v[228:231], v[64:67]
	s_barrier
	s_setprio 0
	s_add_i32 s57, s82, s73
	v_lshl_add_u64 v[192:193], s[12:13], 0, v[146:147]
	s_mov_b32 m0, s57
	ds_read_b128 v[200:203], v185 offset:16384
	ds_read_b128 v[204:207], v185 offset:17408
	ds_read_b128 v[208:211], v185 offset:18432
	ds_read_b128 v[212:215], v185 offset:19456
	ds_read_b128 v[216:219], v185 offset:20480
	ds_read_b128 v[220:223], v185 offset:21504
	ds_read_b128 v[224:227], v185 offset:22528
	ds_read_b128 v[228:231], v185 offset:23552
	global_load_lds_dwordx4 v[192:193], off
	s_add_i32 m0, s57, 0x2000
	s_add_u32 s66, s12, 0x80000
	v_lshl_add_u64 v[232:233], s[12:13], 0, v[150:151]
	s_addc_u32 s67, s13, 0
	s_add_i32 s57, s83, s73
	global_load_lds_dwordx4 v[232:233], off
	v_lshl_add_u64 v[234:235], s[66:67], 0, v[146:147]
	s_mov_b32 m0, s57
	v_lshl_add_u64 v[236:237], s[58:59], 0, v[148:149]
	global_load_lds_dwordx4 v[234:235], off
	v_lshl_add_u64 v[234:235], s[66:67], 0, v[150:151]
	s_add_i32 m0, s57, 0x2000
	s_nop 0
	global_load_lds_dwordx4 v[234:235], off
	v_lshl_add_u64 v[234:235], s[58:59], 0, v[144:145]
	s_mov_b32 m0, s74
	s_nop 0
	global_load_lds_dwordx4 v[234:235], off
	s_mov_b32 m0, s75
	s_nop 0
	global_load_lds_dwordx4 v[236:237], off
	s_waitcnt vmcnt(8)
	s_waitcnt lgkmcnt(0)
	s_setprio 1
	s_barrier
; #define PG8_STAGE(bufoff, gbase, voff) do { _Pragma("unroll") for (int _i = 0; _i < 2; ++_i) \
;         __builtin_amdgcn_global_load_lds((const unsigned*)((const char*)(gbase) + (voff)[_i]), (PG8_LAS unsigned*)(lds + (bufoff) + ldsw + _i * 8192), 16, 0, 0); } while (0)
; #define PG8_LDA(dst, b, h) do { _Pragma("unroll") for (int m = 0; m < 4; ++m) _Pragma("unroll") for (int k = 0; k < 2; ++k) dst[m][k] = *(const PG8_LAS bf16x8*)(lds + PG8_SA(b, h) + aoff + m * 2048 + k * 1024); } while (0)
; #define PG8_LDB(dst, b, h) do { _Pragma("unroll") for (int n = 0; n < 2; ++n) _Pragma("unroll") for (int k = 0; k < 2; ++k) dst[n][k] = *(const PG8_LAS bf16x8*)(lds + PG8_SB(b, h) + boff + n * 2048 + k * 1024); } while (0)
; #define PG8_MMA(ai, bj, At, Bt) do { __builtin_amdgcn_s_setprio(1); _Pragma("unroll") for (int m = 0; m < 4; ++m) _Pragma("unroll") for (int n = 0; n < 2; ++n) _Pragma("unroll") for (int k = 0; k < 2; ++k) \
;         acc[ai][bj][m][n] = __builtin_amdgcn_mfma_f32_16x16x32_bf16(Bt[n][k], At[m][k], acc[ai][bj][m][n], 0, 0, 0); __builtin_amdgcn_s_setprio(0); } while (0)
; #define PG8_WAIT_V(n) asm volatile("s_waitcnt vmcnt(" #n ")" ::: "memory")
; #define PG8_WAIT_L(n) asm volatile("s_waitcnt lgkmcnt(" #n ")" ::: "memory")
; #define PG8_BAR __builtin_amdgcn_s_barrier()
; #define PG8_SCHED __builtin_amdgcn_sched_barrier(0)
; template <class Epi, class Sched, bool ALIGN_EPI = false, bool SP2 = false>
; __device__ __forceinline__ void gemm_phase(PG8_LAS unsigned char* lds, const Gemm g, const Sched& S, const Epi& E) {
;     ...
;             PG8_WAIT_V(8); PG8_WAIT_L(0); PG8_BAR; PG8_MMA(1, 0, At, B0); PG8_MMA(1, 1, At, B1); PG8_BAR; PG8_SCHED;
;             PG8_LDB(B0, 1, 0); PG8_LDB(B1, 1, 1); PG8_SCHED; PG8_LDA(At, 1, 0); PG8_STAGE(PG8_SA(0, 1), a2 + hstepA, voffA);
;             PG8_WAIT_V(8); PG8_WAIT_L(0); PG8_BAR; PG8_MMA(0, 0, At, B0); PG8_MMA(0, 1, At, B1); PG8_BAR; PG8_SCHED;
	v_mfma_f32_16x16x32_bf16 v[60:63], v[128:131], v[200:203], v[60:63]
	v_mfma_f32_16x16x32_bf16 v[56:59], v[136:139], v[200:203], v[56:59]
	v_mfma_f32_16x16x32_bf16 v[52:55], v[128:131], v[208:211], v[52:55]
	v_mfma_f32_16x16x32_bf16 v[48:51], v[136:139], v[208:211], v[48:51]
	v_mfma_f32_16x16x32_bf16 v[36:39], v[128:131], v[216:219], v[36:39]
	v_mfma_f32_16x16x32_bf16 v[32:35], v[136:139], v[216:219], v[32:35]
	v_mfma_f32_16x16x32_bf16 v[20:23], v[128:131], v[224:227], v[20:23]
	v_mfma_f32_16x16x32_bf16 v[16:19], v[136:139], v[224:227], v[16:19]
	v_mfma_f32_16x16x32_bf16 v[60:63], v[132:135], v[204:207], v[60:63]
	v_mfma_f32_16x16x32_bf16 v[56:59], v[140:143], v[204:207], v[56:59]
	v_mfma_f32_16x16x32_bf16 v[52:55], v[132:135], v[212:215], v[52:55]
	v_mfma_f32_16x16x32_bf16 v[48:51], v[140:143], v[212:215], v[48:51]
	v_mfma_f32_16x16x32_bf16 v[36:39], v[132:135], v[220:223], v[36:39]
	v_mfma_f32_16x16x32_bf16 v[32:35], v[140:143], v[220:223], v[32:35]
	v_mfma_f32_16x16x32_bf16 v[20:23], v[132:135], v[228:231], v[20:23]
	v_mfma_f32_16x16x32_bf16 v[16:19], v[140:143], v[228:231], v[16:19]
	s_setprio 0
	s_setprio 1
	v_mfma_f32_16x16x32_bf16 v[44:47], v[166:169], v[200:203], v[44:47]
	v_mfma_f32_16x16x32_bf16 v[40:43], v[188:191], v[200:203], v[40:43]
	v_mfma_f32_16x16x32_bf16 v[28:31], v[166:169], v[208:211], v[28:31]
	v_mfma_f32_16x16x32_bf16 v[24:27], v[188:191], v[208:211], v[24:27]
	v_mfma_f32_16x16x32_bf16 v[12:15], v[166:169], v[216:219], v[12:15]
	v_mfma_f32_16x16x32_bf16 v[8:11], v[188:191], v[216:219], v[8:11]
	v_mfma_f32_16x16x32_bf16 v[4:7], v[166:169], v[224:227], v[4:7]
	v_mfma_f32_16x16x32_bf16 v[0:3], v[188:191], v[224:227], v[0:3]
	v_mfma_f32_16x16x32_bf16 v[44:47], v[170:173], v[204:207], v[44:47]
	v_mfma_f32_16x16x32_bf16 v[40:43], v[196:199], v[204:207], v[40:43]
	v_mfma_f32_16x16x32_bf16 v[28:31], v[170:173], v[212:215], v[28:31]
	v_mfma_f32_16x16x32_bf16 v[24:27], v[196:199], v[212:215], v[24:27]
	v_mfma_f32_16x16x32_bf16 v[12:15], v[170:173], v[220:223], v[12:15]
	v_mfma_f32_16x16x32_bf16 v[8:11], v[196:199], v[220:223], v[8:11]
	v_mfma_f32_16x16x32_bf16 v[4:7], v[170:173], v[228:231], v[4:7]
	v_mfma_f32_16x16x32_bf16 v[0:3], v[196:199], v[228:231], v[0:3]
	s_barrier
	s_setprio 0
	s_add_i32 s57, 0, 0x18000
	s_add_i32 s66, 0, 0x1c000
	v_add_u32_e32 v140, s57, v177
	v_add_u32_e32 v152, s66, v177
	ds_read_b128 v[128:131], v140
	ds_read_b128 v[132:135], v140 offset:1024
	ds_read_b128 v[136:139], v140 offset:2048
	ds_read_b128 v[140:143], v140 offset:3072
	ds_read_b128 v[166:169], v152
	ds_read_b128 v[170:173], v152 offset:1024
	ds_read_b128 v[188:191], v152 offset:2048
	ds_read_b128 v[196:199], v152 offset:3072
	s_add_u32 s58, s58, 0x80000
	s_addc_u32 s59, s59, 0
	s_mov_b32 m0, s76
	v_lshl_add_u64 v[238:239], s[58:59], 0, v[144:145]
	ds_read_b128 v[200:203], v185 offset:32768
	ds_read_b128 v[204:207], v185 offset:33792
	ds_read_b128 v[208:211], v185 offset:34816
	ds_read_b128 v[212:215], v185 offset:35840
	ds_read_b128 v[216:219], v185 offset:36864
	ds_read_b128 v[220:223], v185 offset:37888
	ds_read_b128 v[224:227], v185 offset:38912
	ds_read_b128 v[228:231], v185 offset:39936
	global_load_lds_dwordx4 v[238:239], off
	v_lshl_add_u64 v[238:239], s[58:59], 0, v[148:149]
	s_mov_b32 m0, s77
	s_nop 0
	global_load_lds_dwordx4 v[238:239], off
	s_waitcnt vmcnt(8)
	s_waitcnt lgkmcnt(0)
	s_setprio 1
	s_barrier
	v_mfma_f32_16x16x32_bf16 v[124:127], v[128:131], v[200:203], v[124:127]
	v_mfma_f32_16x16x32_bf16 v[120:123], v[136:139], v[200:203], v[120:123]
	v_mfma_f32_16x16x32_bf16 v[116:119], v[128:131], v[208:211], v[116:119]
	v_mfma_f32_16x16x32_bf16 v[112:115], v[136:139], v[208:211], v[112:115]
	v_mfma_f32_16x16x32_bf16 v[100:103], v[128:131], v[216:219], v[100:103]
	v_mfma_f32_16x16x32_bf16 v[96:99], v[136:139], v[216:219], v[96:99]
	v_mfma_f32_16x16x32_bf16 v[84:87], v[128:131], v[224:227], v[84:87]
	v_mfma_f32_16x16x32_bf16 v[80:83], v[136:139], v[224:227], v[80:83]
	v_mfma_f32_16x16x32_bf16 v[124:127], v[132:135], v[204:207], v[124:127]
	v_mfma_f32_16x16x32_bf16 v[120:123], v[140:143], v[204:207], v[120:123]
	v_mfma_f32_16x16x32_bf16 v[116:119], v[132:135], v[212:215], v[116:119]
	v_mfma_f32_16x16x32_bf16 v[112:115], v[140:143], v[212:215], v[112:115]
	v_mfma_f32_16x16x32_bf16 v[100:103], v[132:135], v[220:223], v[100:103]
	v_mfma_f32_16x16x32_bf16 v[96:99], v[140:143], v[220:223], v[96:99]
	v_mfma_f32_16x16x32_bf16 v[84:87], v[132:135], v[228:231], v[84:87]
	v_mfma_f32_16x16x32_bf16 v[80:83], v[140:143], v[228:231], v[80:83]
	s_setprio 0
	s_setprio 1
	v_mfma_f32_16x16x32_bf16 v[108:111], v[166:169], v[200:203], v[108:111]
	v_mfma_f32_16x16x32_bf16 v[104:107], v[188:191], v[200:203], v[104:107]
	v_mfma_f32_16x16x32_bf16 v[92:95], v[166:169], v[208:211], v[92:95]
	v_mfma_f32_16x16x32_bf16 v[88:91], v[188:191], v[208:211], v[88:91]
	v_mfma_f32_16x16x32_bf16 v[76:79], v[166:169], v[216:219], v[76:79]
	v_mfma_f32_16x16x32_bf16 v[72:75], v[188:191], v[216:219], v[72:75]
	v_mfma_f32_16x16x32_bf16 v[68:71], v[166:169], v[224:227], v[68:71]
	v_mfma_f32_16x16x32_bf16 v[64:67], v[188:191], v[224:227], v[64:67]
	v_mfma_f32_16x16x32_bf16 v[108:111], v[170:173], v[204:207], v[108:111]
	v_mfma_f32_16x16x32_bf16 v[104:107], v[196:199], v[204:207], v[104:107]
	v_mfma_f32_16x16x32_bf16 v[92:95], v[170:173], v[212:215], v[92:95]
	v_mfma_f32_16x16x32_bf16 v[88:91], v[196:199], v[212:215], v[88:91]
	v_mfma_f32_16x16x32_bf16 v[76:79], v[170:173], v[220:223], v[76:79]
	v_mfma_f32_16x16x32_bf16 v[72:75], v[196:199], v[220:223], v[72:75]
	v_mfma_f32_16x16x32_bf16 v[68:71], v[170:173], v[228:231], v[68:71]
	v_mfma_f32_16x16x32_bf16 v[64:67], v[196:199], v[228:231], v[64:67]
	s_barrier
; #define PG8_STAGE(bufoff, gbase, voff) do { _Pragma("unroll") for (int _i = 0; _i < 2; ++_i) \
;         __builtin_amdgcn_global_load_lds((const unsigned*)((const char*)(gbase) + (voff)[_i]), (PG8_LAS unsigned*)(lds + (bufoff) + ldsw + _i * 8192), 16, 0, 0); } while (0)
; #define PG8_LDA(dst, b, h) do { _Pragma("unroll") for (int m = 0; m < 4; ++m) _Pragma("unroll") for (int k = 0; k < 2; ++k) dst[m][k] = *(const PG8_LAS bf16x8*)(lds + PG8_SA(b, h) + aoff + m * 2048 + k * 1024); } while (0)
; #define PG8_MMA(ai, bj, At, Bt) do { __builtin_amdgcn_s_setprio(1); _Pragma("unroll") for (int m = 0; m < 4; ++m) _Pragma("unroll") for (int n = 0; n < 2; ++n) _Pragma("unroll") for (int k = 0; k < 2; ++k) \
;         acc[ai][bj][m][n] = __builtin_amdgcn_mfma_f32_16x16x32_bf16(Bt[n][k], At[m][k], acc[ai][bj][m][n], 0, 0, 0); __builtin_amdgcn_s_setprio(0); } while (0)
; #define PG8_WAIT_V(n) asm volatile("s_waitcnt vmcnt(" #n ")" ::: "memory")
; #define PG8_WAIT_L(n) asm volatile("s_waitcnt lgkmcnt(" #n ")" ::: "memory")
; #define PG8_BAR __builtin_amdgcn_s_barrier()
; #define PG8_SCHED __builtin_amdgcn_sched_barrier(0)
; template <class Epi, class Sched, bool ALIGN_EPI = false, bool SP2 = false>
; __device__ __forceinline__ void gemm_phase(PG8_LAS unsigned char* lds, const Gemm g, const Sched& S, const Epi& E) {
;     ...
;             PG8_LDA(At, 1, 1); PG8_STAGE(PG8_SB(1, 0), b3, voffB); PG8_STAGE(PG8_SB(1, 1), b3 + hstepB, voffB); PG8_STAGE(PG8_SA(1, 0), a3, voffA);
;             PG8_WAIT_V(8); PG8_WAIT_L(0); PG8_BAR; PG8_MMA(1, 0, At, B0); PG8_MMA(1, 1, At, B1); PG8_BAR; PG8_SCHED;
;     ...
;         if constexpr (ALIGN_EPI) { if (wr == 0) PG8_BAR; }
	s_setprio 0
	s_add_i32 s57, s57, s73
	v_lshl_add_u64 v[192:193], v[192:193], 0, s[42:43]
	s_mov_b32 m0, s57
	ds_read_b128 v[200:203], v185 offset:49152
	ds_read_b128 v[204:207], v185 offset:50176
	ds_read_b128 v[208:211], v185 offset:51200
	ds_read_b128 v[212:215], v185 offset:52224
	ds_read_b128 v[216:219], v185 offset:53248
	ds_read_b128 v[220:223], v185 offset:54272
	ds_read_b128 v[224:227], v185 offset:55296
	ds_read_b128 v[228:231], v185 offset:56320
	global_load_lds_dwordx4 v[192:193], off
	s_add_i32 m0, s57, 0x2000
	s_add_u32 s12, s12, 0x80080
	v_lshl_add_u64 v[192:193], v[232:233], 0, s[42:43]
	s_addc_u32 s13, s13, 0
	s_add_i32 s57, s66, s73
	global_load_lds_dwordx4 v[192:193], off
	v_lshl_add_u64 v[192:193], s[12:13], 0, v[146:147]
	s_mov_b32 m0, s57
	s_nop 0
	global_load_lds_dwordx4 v[192:193], off
	v_lshl_add_u64 v[192:193], s[12:13], 0, v[150:151]
	s_add_i32 m0, s57, 0x2000
	s_nop 0
	global_load_lds_dwordx4 v[192:193], off
	v_lshl_add_u64 v[192:193], v[234:235], 0, s[42:43]
	s_mov_b32 m0, s80
	s_nop 0
	global_load_lds_dwordx4 v[192:193], off
	v_lshl_add_u64 v[192:193], v[236:237], 0, s[42:43]
	s_mov_b32 m0, s81
	s_nop 0
	global_load_lds_dwordx4 v[192:193], off
	s_waitcnt vmcnt(8)
	s_waitcnt lgkmcnt(0)
	s_setprio 1
	s_barrier
	v_mfma_f32_16x16x32_bf16 v[60:63], v[128:131], v[200:203], v[60:63]
	v_mfma_f32_16x16x32_bf16 v[56:59], v[136:139], v[200:203], v[56:59]
	v_mfma_f32_16x16x32_bf16 v[52:55], v[128:131], v[208:211], v[52:55]
	v_mfma_f32_16x16x32_bf16 v[48:51], v[136:139], v[208:211], v[48:51]
	v_mfma_f32_16x16x32_bf16 v[36:39], v[128:131], v[216:219], v[36:39]
	v_mfma_f32_16x16x32_bf16 v[32:35], v[136:139], v[216:219], v[32:35]
	v_mfma_f32_16x16x32_bf16 v[20:23], v[128:131], v[224:227], v[20:23]
	v_mfma_f32_16x16x32_bf16 v[16:19], v[136:139], v[224:227], v[16:19]
	v_mfma_f32_16x16x32_bf16 v[60:63], v[132:135], v[204:207], v[60:63]
	v_mfma_f32_16x16x32_bf16 v[56:59], v[140:143], v[204:207], v[56:59]
	v_mfma_f32_16x16x32_bf16 v[52:55], v[132:135], v[212:215], v[52:55]
	v_mfma_f32_16x16x32_bf16 v[48:51], v[140:143], v[212:215], v[48:51]
	v_mfma_f32_16x16x32_bf16 v[36:39], v[132:135], v[220:223], v[36:39]
	v_mfma_f32_16x16x32_bf16 v[32:35], v[140:143], v[220:223], v[32:35]
	v_mfma_f32_16x16x32_bf16 v[20:23], v[132:135], v[228:231], v[20:23]
	v_mfma_f32_16x16x32_bf16 v[16:19], v[140:143], v[228:231], v[16:19]
	s_setprio 0
	s_setprio 1
	v_mfma_f32_16x16x32_bf16 v[44:47], v[166:169], v[200:203], v[44:47]
	v_mfma_f32_16x16x32_bf16 v[40:43], v[188:191], v[200:203], v[40:43]
	v_mfma_f32_16x16x32_bf16 v[28:31], v[166:169], v[208:211], v[28:31]
	v_mfma_f32_16x16x32_bf16 v[24:27], v[188:191], v[208:211], v[24:27]
	v_mfma_f32_16x16x32_bf16 v[12:15], v[166:169], v[216:219], v[12:15]
	v_mfma_f32_16x16x32_bf16 v[8:11], v[188:191], v[216:219], v[8:11]
	v_mfma_f32_16x16x32_bf16 v[4:7], v[166:169], v[224:227], v[4:7]
	v_mfma_f32_16x16x32_bf16 v[0:3], v[188:191], v[224:227], v[0:3]
	v_mfma_f32_16x16x32_bf16 v[44:47], v[170:173], v[204:207], v[44:47]
	v_mfma_f32_16x16x32_bf16 v[40:43], v[196:199], v[204:207], v[40:43]
	v_mfma_f32_16x16x32_bf16 v[28:31], v[170:173], v[212:215], v[28:31]
	v_mfma_f32_16x16x32_bf16 v[24:27], v[196:199], v[212:215], v[24:27]
	v_mfma_f32_16x16x32_bf16 v[12:15], v[170:173], v[220:223], v[12:15]
	v_mfma_f32_16x16x32_bf16 v[8:11], v[196:199], v[220:223], v[8:11]
	v_mfma_f32_16x16x32_bf16 v[4:7], v[170:173], v[228:231], v[4:7]
	v_mfma_f32_16x16x32_bf16 v[0:3], v[196:199], v[228:231], v[0:3]
	s_barrier
	s_setprio 0
	s_add_i32 s55, s55, 2
	s_add_u32 s10, s10, 0x100
	s_addc_u32 s11, s11, 0
	s_add_u32 s9, s9, 0x100
	s_addc_u32 s33, s33, 0
	s_cmp_gt_u32 s55, 29
	s_cbranch_scc0 .LBB0_177
	s_and_b64 vcc, exec, s[44:45]
	s_cbranch_vccz .LBB0_180
	s_barrier

; #define PG8_STAGE(bufoff, gbase, voff) do { _Pragma("unroll") for (int _i = 0; _i < 2; ++_i) \
;         __builtin_amdgcn_global_load_lds((const unsigned*)((const char*)(gbase) + (voff)[_i]), (PG8_LAS unsigned*)(lds + (bufoff) + ldsw + _i * 8192), 16, 0, 0); } while (0)
; #define PG8_LDA(dst, b, h) do { _Pragma("unroll") for (int m = 0; m < 4; ++m) _Pragma("unroll") for (int k = 0; k < 2; ++k) dst[m][k] = *(const PG8_LAS bf16x8*)(lds + PG8_SA(b, h) + aoff + m * 2048 + k * 1024); } while (0)
; #define PG8_LDB(dst, b, h) do { _Pragma("unroll") for (int n = 0; n < 2; ++n) _Pragma("unroll") for (int k = 0; k < 2; ++k) dst[n][k] = *(const PG8_LAS bf16x8*)(lds + PG8_SB(b, h) + boff + n * 2048 + k * 1024); } while (0)
; #define PG8_MMA(ai, bj, At, Bt) do { __builtin_amdgcn_s_setprio(1); _Pragma("unroll") for (int m = 0; m < 4; ++m) _Pragma("unroll") for (int n = 0; n < 2; ++n) _Pragma("unroll") for (int k = 0; k < 2; ++k) \
;         acc[ai][bj][m][n] = __builtin_amdgcn_mfma_f32_16x16x32_bf16(Bt[n][k], At[m][k], acc[ai][bj][m][n], 0, 0, 0); __builtin_amdgcn_s_setprio(0); } while (0)
; #define PG8_WAIT_V(n) asm volatile("s_waitcnt vmcnt(" #n ")" ::: "memory")
; #define PG8_WAIT_L(n) asm volatile("s_waitcnt lgkmcnt(" #n ")" ::: "memory")
; #define PG8_BAR __builtin_amdgcn_s_barrier()
; #define PG8_SCHED __builtin_amdgcn_sched_barrier(0)
; template <class Epi, class Sched, bool ALIGN_EPI = false, bool SP2 = false>
; __device__ __forceinline__ void gemm_phase(PG8_LAS unsigned char* lds, const Gemm g, const Sched& S, const Epi& E) {
;     ...
;             PG8_LDB(B0, 0, 0); PG8_LDB(B1, 0, 1); PG8_SCHED; PG8_LDA(At, 0, 0); PG8_STAGE(PG8_SA(1, 1), a1 + hstepA, voffA);
;             PG8_WAIT_V(8); PG8_WAIT_L(0); PG8_BAR; PG8_MMA(0, 0, At, B0); PG8_MMA(0, 1, At, B1); PG8_BAR; PG8_SCHED;
;             PG8_LDA(At, 0, 1); PG8_STAGE(PG8_SB(0, 0), b2, voffB); PG8_STAGE(PG8_SB(0, 1), b2 + hstepB, voffB); PG8_STAGE(PG8_SA(0, 0), a2, voffA);
;             PG8_WAIT_V(8); PG8_WAIT_L(0); PG8_BAR; PG8_MMA(1, 0, At, B0); PG8_MMA(1, 1, At, B1); PG8_BAR; PG8_SCHED;
.LBB0_521:
	ds_read_b128 v[144:147], v151
	ds_read_b128 v[154:157], v151 offset:1024
	ds_read_b128 v[158:161], v151 offset:2048
	ds_read_b128 v[170:173], v151 offset:3072
	ds_read_b128 v[174:177], v152
	ds_read_b128 v[178:181], v152 offset:1024
	ds_read_b128 v[182:185], v152 offset:2048
	ds_read_b128 v[186:189], v152 offset:3072
	s_add_u32 s36, s34, 0xfffc0080
	s_addc_u32 s37, s35, -1
	s_cmp_eq_u32 s52, 12
	s_cselect_b32 s39, s25, s37
	s_cselect_b32 s38, s48, s36
	s_cselect_b32 s37, s23, s51
	s_cselect_b32 s36, s49, s50
	v_lshl_add_u64 v[224:225], s[34:35], 0, v[136:137]
	s_add_i32 m0, s31, 0xc000
	ds_read_b128 v[190:193], v153
	ds_read_b128 v[196:199], v153 offset:1024
	ds_read_b128 v[200:203], v153 offset:2048
	ds_read_b128 v[204:207], v153 offset:3072
	ds_read_b128 v[208:211], v153 offset:4096
	ds_read_b128 v[212:215], v153 offset:5120
	ds_read_b128 v[216:219], v153 offset:6144
	ds_read_b128 v[220:223], v153 offset:7168
	global_load_lds_dwordx4 v[224:225], off
	v_lshl_add_u64 v[224:225], s[34:35], 0, v[138:139]
	s_add_i32 m0, s31, 0xe000
	s_nop 0
	global_load_lds_dwordx4 v[224:225], off
	s_waitcnt vmcnt(8)
	s_waitcnt lgkmcnt(0)
	s_setprio 1
	s_barrier
	v_mfma_f32_16x16x32_bf16 v[124:127], v[144:147], v[190:193], v[124:127]
	v_mfma_f32_16x16x32_bf16 v[120:123], v[158:161], v[190:193], v[120:123]
	v_mfma_f32_16x16x32_bf16 v[108:111], v[144:147], v[200:203], v[108:111]
	v_mfma_f32_16x16x32_bf16 v[104:107], v[158:161], v[200:203], v[104:107]
	v_mfma_f32_16x16x32_bf16 v[92:95], v[144:147], v[208:211], v[92:95]
	v_mfma_f32_16x16x32_bf16 v[88:91], v[158:161], v[208:211], v[88:91]
	v_mfma_f32_16x16x32_bf16 v[76:79], v[144:147], v[216:219], v[76:79]
	v_mfma_f32_16x16x32_bf16 v[72:75], v[158:161], v[216:219], v[72:75]
	v_mfma_f32_16x16x32_bf16 v[124:127], v[154:157], v[196:199], v[124:127]
	v_mfma_f32_16x16x32_bf16 v[120:123], v[170:173], v[196:199], v[120:123]
	v_mfma_f32_16x16x32_bf16 v[108:111], v[154:157], v[204:207], v[108:111]
	v_mfma_f32_16x16x32_bf16 v[104:107], v[170:173], v[204:207], v[104:107]
	v_mfma_f32_16x16x32_bf16 v[92:95], v[154:157], v[212:215], v[92:95]
	v_mfma_f32_16x16x32_bf16 v[88:91], v[170:173], v[212:215], v[88:91]
	v_mfma_f32_16x16x32_bf16 v[76:79], v[154:157], v[220:223], v[76:79]
	v_mfma_f32_16x16x32_bf16 v[72:75], v[170:173], v[220:223], v[72:75]
	s_setprio 0
	s_setprio 1
	v_mfma_f32_16x16x32_bf16 v[116:119], v[174:177], v[190:193], v[116:119]
	v_mfma_f32_16x16x32_bf16 v[112:115], v[182:185], v[190:193], v[112:115]
	v_mfma_f32_16x16x32_bf16 v[100:103], v[174:177], v[200:203], v[100:103]
	v_mfma_f32_16x16x32_bf16 v[96:99], v[182:185], v[200:203], v[96:99]
	v_mfma_f32_16x16x32_bf16 v[84:87], v[174:177], v[208:211], v[84:87]
	v_mfma_f32_16x16x32_bf16 v[80:83], v[182:185], v[208:211], v[80:83]
	v_mfma_f32_16x16x32_bf16 v[68:71], v[174:177], v[216:219], v[68:71]
	v_mfma_f32_16x16x32_bf16 v[64:67], v[182:185], v[216:219], v[64:67]
	v_mfma_f32_16x16x32_bf16 v[116:119], v[178:181], v[196:199], v[116:119]
	v_mfma_f32_16x16x32_bf16 v[112:115], v[186:189], v[196:199], v[112:115]
	v_mfma_f32_16x16x32_bf16 v[100:103], v[178:181], v[204:207], v[100:103]
	v_mfma_f32_16x16x32_bf16 v[96:99], v[186:189], v[204:207], v[96:99]
	v_mfma_f32_16x16x32_bf16 v[84:87], v[178:181], v[212:215], v[84:87]
	v_mfma_f32_16x16x32_bf16 v[80:83], v[186:189], v[212:215], v[80:83]
	v_mfma_f32_16x16x32_bf16 v[68:71], v[178:181], v[220:223], v[68:71]
	v_mfma_f32_16x16x32_bf16 v[64:67], v[186:189], v[220:223], v[64:67]
	s_barrier
	s_setprio 0
	s_add_i32 s53, s56, s33
	v_lshl_add_u64 v[224:225], s[36:37], 0, v[132:133]
	s_mov_b32 m0, s53
	ds_read_b128 v[190:193], v153 offset:16384
	ds_read_b128 v[196:199], v153 offset:17408
	ds_read_b128 v[200:203], v153 offset:18432
	ds_read_b128 v[204:207], v153 offset:19456
	ds_read_b128 v[208:211], v153 offset:20480
	ds_read_b128 v[212:215], v153 offset:21504
	ds_read_b128 v[216:219], v153 offset:22528
	ds_read_b128 v[220:223], v153 offset:23552
	global_load_lds_dwordx4 v[224:225], off
	s_add_i32 m0, s53, 0x2000
	s_add_u32 s54, s36, 0x40000
	v_lshl_add_u64 v[226:227], s[36:37], 0, v[128:129]
	s_addc_u32 s55, s37, 0
	s_add_i32 s53, s46, s33
	global_load_lds_dwordx4 v[226:227], off
	v_lshl_add_u64 v[228:229], s[54:55], 0, v[132:133]
	s_mov_b32 m0, s53
	v_lshl_add_u64 v[230:231], s[38:39], 0, v[130:131]
	global_load_lds_dwordx4 v[228:229], off
	v_lshl_add_u64 v[228:229], s[54:55], 0, v[128:129]
	s_add_i32 m0, s53, 0x2000
	s_nop 0
	global_load_lds_dwordx4 v[228:229], off
	v_lshl_add_u64 v[228:229], s[38:39], 0, v[134:135]
	s_mov_b32 m0, s31
	s_nop 0
	global_load_lds_dwordx4 v[228:229], off
	s_mov_b32 m0, s40
	s_nop 0
	global_load_lds_dwordx4 v[230:231], off
	s_waitcnt vmcnt(8)
	s_waitcnt lgkmcnt(0)
	s_setprio 1
	s_barrier
; #define PG8_STAGE(bufoff, gbase, voff) do { _Pragma("unroll") for (int _i = 0; _i < 2; ++_i) \
;         __builtin_amdgcn_global_load_lds((const unsigned*)((const char*)(gbase) + (voff)[_i]), (PG8_LAS unsigned*)(lds + (bufoff) + ldsw + _i * 8192), 16, 0, 0); } while (0)
; #define PG8_LDA(dst, b, h) do { _Pragma("unroll") for (int m = 0; m < 4; ++m) _Pragma("unroll") for (int k = 0; k < 2; ++k) dst[m][k] = *(const PG8_LAS bf16x8*)(lds + PG8_SA(b, h) + aoff + m * 2048 + k * 1024); } while (0)
; #define PG8_LDB(dst, b, h) do { _Pragma("unroll") for (int n = 0; n < 2; ++n) _Pragma("unroll") for (int k = 0; k < 2; ++k) dst[n][k] = *(const PG8_LAS bf16x8*)(lds + PG8_SB(b, h) + boff + n * 2048 + k * 1024); } while (0)
; #define PG8_MMA(ai, bj, At, Bt) do { __builtin_amdgcn_s_setprio(1); _Pragma("unroll") for (int m = 0; m < 4; ++m) _Pragma("unroll") for (int n = 0; n < 2; ++n) _Pragma("unroll") for (int k = 0; k < 2; ++k) \
;         acc[ai][bj][m][n] = __builtin_amdgcn_mfma_f32_16x16x32_bf16(Bt[n][k], At[m][k], acc[ai][bj][m][n], 0, 0, 0); __builtin_amdgcn_s_setprio(0); } while (0)
; #define PG8_WAIT_V(n) asm volatile("s_waitcnt vmcnt(" #n ")" ::: "memory")
; #define PG8_WAIT_L(n) asm volatile("s_waitcnt lgkmcnt(" #n ")" ::: "memory")
; #define PG8_BAR __builtin_amdgcn_s_barrier()
; #define PG8_SCHED __builtin_amdgcn_sched_barrier(0)
; template <class Epi, class Sched, bool ALIGN_EPI = false, bool SP2 = false>
; __device__ __forceinline__ void gemm_phase(PG8_LAS unsigned char* lds, const Gemm g, const Sched& S, const Epi& E) {
;     ...
;             PG8_WAIT_V(8); PG8_WAIT_L(0); PG8_BAR; PG8_MMA(1, 0, At, B0); PG8_MMA(1, 1, At, B1); PG8_BAR; PG8_SCHED;
;             PG8_LDB(B0, 1, 0); PG8_LDB(B1, 1, 1); PG8_SCHED; PG8_LDA(At, 1, 0); PG8_STAGE(PG8_SA(0, 1), a2 + hstepA, voffA);
;             PG8_WAIT_V(8); PG8_WAIT_L(0); PG8_BAR; PG8_MMA(0, 0, At, B0); PG8_MMA(0, 1, At, B1); PG8_BAR; PG8_SCHED;
	v_mfma_f32_16x16x32_bf16 v[60:63], v[144:147], v[190:193], v[60:63]
	v_mfma_f32_16x16x32_bf16 v[56:59], v[158:161], v[190:193], v[56:59]
	v_mfma_f32_16x16x32_bf16 v[44:47], v[144:147], v[200:203], v[44:47]
	v_mfma_f32_16x16x32_bf16 v[40:43], v[158:161], v[200:203], v[40:43]
	v_mfma_f32_16x16x32_bf16 v[28:31], v[144:147], v[208:211], v[28:31]
	v_mfma_f32_16x16x32_bf16 v[24:27], v[158:161], v[208:211], v[24:27]
	v_mfma_f32_16x16x32_bf16 v[12:15], v[144:147], v[216:219], v[12:15]
	v_mfma_f32_16x16x32_bf16 v[8:11], v[158:161], v[216:219], v[8:11]
	v_mfma_f32_16x16x32_bf16 v[60:63], v[154:157], v[196:199], v[60:63]
	v_mfma_f32_16x16x32_bf16 v[56:59], v[170:173], v[196:199], v[56:59]
	v_mfma_f32_16x16x32_bf16 v[44:47], v[154:157], v[204:207], v[44:47]
	v_mfma_f32_16x16x32_bf16 v[40:43], v[170:173], v[204:207], v[40:43]
	v_mfma_f32_16x16x32_bf16 v[28:31], v[154:157], v[212:215], v[28:31]
	v_mfma_f32_16x16x32_bf16 v[24:27], v[170:173], v[212:215], v[24:27]
	v_mfma_f32_16x16x32_bf16 v[12:15], v[154:157], v[220:223], v[12:15]
	v_mfma_f32_16x16x32_bf16 v[8:11], v[170:173], v[220:223], v[8:11]
	s_setprio 0
	s_setprio 1
	v_mfma_f32_16x16x32_bf16 v[52:55], v[174:177], v[190:193], v[52:55]
	v_mfma_f32_16x16x32_bf16 v[48:51], v[182:185], v[190:193], v[48:51]
	v_mfma_f32_16x16x32_bf16 v[36:39], v[174:177], v[200:203], v[36:39]
	v_mfma_f32_16x16x32_bf16 v[32:35], v[182:185], v[200:203], v[32:35]
	v_mfma_f32_16x16x32_bf16 v[20:23], v[174:177], v[208:211], v[20:23]
	v_mfma_f32_16x16x32_bf16 v[16:19], v[182:185], v[208:211], v[16:19]
	v_mfma_f32_16x16x32_bf16 v[4:7], v[174:177], v[216:219], v[4:7]
	v_mfma_f32_16x16x32_bf16 v[0:3], v[182:185], v[216:219], v[0:3]
	v_mfma_f32_16x16x32_bf16 v[52:55], v[178:181], v[196:199], v[52:55]
	v_mfma_f32_16x16x32_bf16 v[48:51], v[186:189], v[196:199], v[48:51]
	v_mfma_f32_16x16x32_bf16 v[36:39], v[178:181], v[204:207], v[36:39]
	v_mfma_f32_16x16x32_bf16 v[32:35], v[186:189], v[204:207], v[32:35]
	v_mfma_f32_16x16x32_bf16 v[20:23], v[178:181], v[212:215], v[20:23]
	v_mfma_f32_16x16x32_bf16 v[16:19], v[186:189], v[212:215], v[16:19]
	v_mfma_f32_16x16x32_bf16 v[4:7], v[178:181], v[220:223], v[4:7]
	v_mfma_f32_16x16x32_bf16 v[0:3], v[186:189], v[220:223], v[0:3]
	s_barrier
	s_setprio 0
	s_add_i32 s53, 0, 0x18000
	v_add_u32_e32 v169, s53, v149
	s_add_i32 s54, 0, 0x1c000
	ds_read_b128 v[144:147], v169
	ds_read_b128 v[154:157], v169 offset:1024
	ds_read_b128 v[158:161], v169 offset:2048
	ds_read_b128 v[170:173], v169 offset:3072
	v_add_u32_e32 v169, s54, v149
	ds_read_b128 v[174:177], v169
	ds_read_b128 v[178:181], v169 offset:1024
	ds_read_b128 v[182:185], v169 offset:2048
	ds_read_b128 v[186:189], v169 offset:3072
	s_add_u32 s38, s38, 0x40000
	s_addc_u32 s39, s39, 0
	s_mov_b32 m0, s41
	v_lshl_add_u64 v[232:233], s[38:39], 0, v[134:135]
	ds_read_b128 v[190:193], v153 offset:32768
	ds_read_b128 v[196:199], v153 offset:33792
	ds_read_b128 v[200:203], v153 offset:34816
	ds_read_b128 v[204:207], v153 offset:35840
	ds_read_b128 v[208:211], v153 offset:36864
	ds_read_b128 v[212:215], v153 offset:37888
	ds_read_b128 v[216:219], v153 offset:38912
	ds_read_b128 v[220:223], v153 offset:39936
	global_load_lds_dwordx4 v[232:233], off
	v_lshl_add_u64 v[232:233], s[38:39], 0, v[130:131]
	s_mov_b32 m0, s42
	s_nop 0
	global_load_lds_dwordx4 v[232:233], off
	s_waitcnt vmcnt(8)
	s_waitcnt lgkmcnt(0)
	s_setprio 1
	s_barrier
	v_mfma_f32_16x16x32_bf16 v[124:127], v[144:147], v[190:193], v[124:127]
	v_mfma_f32_16x16x32_bf16 v[120:123], v[158:161], v[190:193], v[120:123]
	v_mfma_f32_16x16x32_bf16 v[108:111], v[144:147], v[200:203], v[108:111]
	v_mfma_f32_16x16x32_bf16 v[104:107], v[158:161], v[200:203], v[104:107]
	v_mfma_f32_16x16x32_bf16 v[92:95], v[144:147], v[208:211], v[92:95]
	v_mfma_f32_16x16x32_bf16 v[88:91], v[158:161], v[208:211], v[88:91]
	v_mfma_f32_16x16x32_bf16 v[76:79], v[144:147], v[216:219], v[76:79]
	v_mfma_f32_16x16x32_bf16 v[72:75], v[158:161], v[216:219], v[72:75]
	v_mfma_f32_16x16x32_bf16 v[124:127], v[154:157], v[196:199], v[124:127]
	v_mfma_f32_16x16x32_bf16 v[120:123], v[170:173], v[196:199], v[120:123]
	v_mfma_f32_16x16x32_bf16 v[108:111], v[154:157], v[204:207], v[108:111]
	v_mfma_f32_16x16x32_bf16 v[104:107], v[170:173], v[204:207], v[104:107]
	v_mfma_f32_16x16x32_bf16 v[92:95], v[154:157], v[212:215], v[92:95]
	v_mfma_f32_16x16x32_bf16 v[88:91], v[170:173], v[212:215], v[88:91]
	v_mfma_f32_16x16x32_bf16 v[76:79], v[154:157], v[220:223], v[76:79]
	v_mfma_f32_16x16x32_bf16 v[72:75], v[170:173], v[220:223], v[72:75]
	s_setprio 0
	s_setprio 1
	v_mfma_f32_16x16x32_bf16 v[116:119], v[174:177], v[190:193], v[116:119]
	v_mfma_f32_16x16x32_bf16 v[112:115], v[182:185], v[190:193], v[112:115]
	v_mfma_f32_16x16x32_bf16 v[100:103], v[174:177], v[200:203], v[100:103]
	v_mfma_f32_16x16x32_bf16 v[96:99], v[182:185], v[200:203], v[96:99]
	v_mfma_f32_16x16x32_bf16 v[84:87], v[174:177], v[208:211], v[84:87]
	v_mfma_f32_16x16x32_bf16 v[80:83], v[182:185], v[208:211], v[80:83]
	v_mfma_f32_16x16x32_bf16 v[68:71], v[174:177], v[216:219], v[68:71]
	v_mfma_f32_16x16x32_bf16 v[64:67], v[182:185], v[216:219], v[64:67]
	v_mfma_f32_16x16x32_bf16 v[116:119], v[178:181], v[196:199], v[116:119]
	v_mfma_f32_16x16x32_bf16 v[112:115], v[186:189], v[196:199], v[112:115]
	v_mfma_f32_16x16x32_bf16 v[100:103], v[178:181], v[204:207], v[100:103]
	v_mfma_f32_16x16x32_bf16 v[96:99], v[186:189], v[204:207], v[96:99]
	v_mfma_f32_16x16x32_bf16 v[84:87], v[178:181], v[212:215], v[84:87]
	v_mfma_f32_16x16x32_bf16 v[80:83], v[186:189], v[212:215], v[80:83]
	v_mfma_f32_16x16x32_bf16 v[68:71], v[178:181], v[220:223], v[68:71]
	v_mfma_f32_16x16x32_bf16 v[64:67], v[186:189], v[220:223], v[64:67]
	s_barrier
; #define PG8_STAGE(bufoff, gbase, voff) do { _Pragma("unroll") for (int _i = 0; _i < 2; ++_i) \
;         __builtin_amdgcn_global_load_lds((const unsigned*)((const char*)(gbase) + (voff)[_i]), (PG8_LAS unsigned*)(lds + (bufoff) + ldsw + _i * 8192), 16, 0, 0); } while (0)
; #define PG8_LDA(dst, b, h) do { _Pragma("unroll") for (int m = 0; m < 4; ++m) _Pragma("unroll") for (int k = 0; k < 2; ++k) dst[m][k] = *(const PG8_LAS bf16x8*)(lds + PG8_SA(b, h) + aoff + m * 2048 + k * 1024); } while (0)
; #define PG8_MMA(ai, bj, At, Bt) do { __builtin_amdgcn_s_setprio(1); _Pragma("unroll") for (int m = 0; m < 4; ++m) _Pragma("unroll") for (int n = 0; n < 2; ++n) _Pragma("unroll") for (int k = 0; k < 2; ++k) \
;         acc[ai][bj][m][n] = __builtin_amdgcn_mfma_f32_16x16x32_bf16(Bt[n][k], At[m][k], acc[ai][bj][m][n], 0, 0, 0); __builtin_amdgcn_s_setprio(0); } while (0)
; #define PG8_WAIT_V(n) asm volatile("s_waitcnt vmcnt(" #n ")" ::: "memory")
; #define PG8_WAIT_L(n) asm volatile("s_waitcnt lgkmcnt(" #n ")" ::: "memory")
; #define PG8_BAR __builtin_amdgcn_s_barrier()
; #define PG8_SCHED __builtin_amdgcn_sched_barrier(0)
; template <class Epi, class Sched, bool ALIGN_EPI = false, bool SP2 = false>
; __device__ __forceinline__ void gemm_phase(PG8_LAS unsigned char* lds, const Gemm g, const Sched& S, const Epi& E) {
;     ...
;             PG8_LDA(At, 1, 1); PG8_STAGE(PG8_SB(1, 0), b3, voffB); PG8_STAGE(PG8_SB(1, 1), b3 + hstepB, voffB); PG8_STAGE(PG8_SA(1, 0), a3, voffA);
;             PG8_WAIT_V(8); PG8_WAIT_L(0); PG8_BAR; PG8_MMA(1, 0, At, B0); PG8_MMA(1, 1, At, B1); PG8_BAR; PG8_SCHED;
;     ...
;         if constexpr (ALIGN_EPI) { if (wr == 0) PG8_BAR; }
	s_setprio 0
	s_add_i32 s38, s53, s33
	v_lshl_add_u64 v[224:225], v[224:225], 0, s[18:19]
	s_mov_b32 m0, s38
	ds_read_b128 v[190:193], v153 offset:49152
	ds_read_b128 v[196:199], v153 offset:50176
	ds_read_b128 v[200:203], v153 offset:51200
	ds_read_b128 v[204:207], v153 offset:52224
	ds_read_b128 v[208:211], v153 offset:53248
	ds_read_b128 v[212:215], v153 offset:54272
	ds_read_b128 v[216:219], v153 offset:55296
	ds_read_b128 v[220:223], v153 offset:56320
	global_load_lds_dwordx4 v[224:225], off
	s_add_i32 m0, s38, 0x2000
	s_add_u32 s36, s36, 0x40080
	v_lshl_add_u64 v[224:225], v[226:227], 0, s[18:19]
	s_addc_u32 s37, s37, 0
	s_add_i32 s38, s54, s33
	global_load_lds_dwordx4 v[224:225], off
	v_lshl_add_u64 v[224:225], s[36:37], 0, v[132:133]
	s_mov_b32 m0, s38
	s_nop 0
	global_load_lds_dwordx4 v[224:225], off
	v_lshl_add_u64 v[224:225], s[36:37], 0, v[128:129]
	s_add_i32 m0, s38, 0x2000
	s_nop 0
	global_load_lds_dwordx4 v[224:225], off
	v_lshl_add_u64 v[224:225], v[228:229], 0, s[18:19]
	s_mov_b32 m0, s43
	s_nop 0
	global_load_lds_dwordx4 v[224:225], off
	v_lshl_add_u64 v[224:225], v[230:231], 0, s[18:19]
	s_mov_b32 m0, s44
	s_nop 0
	global_load_lds_dwordx4 v[224:225], off
	s_waitcnt vmcnt(8)
	s_waitcnt lgkmcnt(0)
	s_setprio 1
	s_barrier
	v_mfma_f32_16x16x32_bf16 v[60:63], v[144:147], v[190:193], v[60:63]
	v_mfma_f32_16x16x32_bf16 v[56:59], v[158:161], v[190:193], v[56:59]
	v_mfma_f32_16x16x32_bf16 v[44:47], v[144:147], v[200:203], v[44:47]
	v_mfma_f32_16x16x32_bf16 v[40:43], v[158:161], v[200:203], v[40:43]
	v_mfma_f32_16x16x32_bf16 v[28:31], v[144:147], v[208:211], v[28:31]
	v_mfma_f32_16x16x32_bf16 v[24:27], v[158:161], v[208:211], v[24:27]
	v_mfma_f32_16x16x32_bf16 v[12:15], v[144:147], v[216:219], v[12:15]
	v_mfma_f32_16x16x32_bf16 v[8:11], v[158:161], v[216:219], v[8:11]
	v_mfma_f32_16x16x32_bf16 v[60:63], v[154:157], v[196:199], v[60:63]
	v_mfma_f32_16x16x32_bf16 v[56:59], v[170:173], v[196:199], v[56:59]
	v_mfma_f32_16x16x32_bf16 v[44:47], v[154:157], v[204:207], v[44:47]
	v_mfma_f32_16x16x32_bf16 v[40:43], v[170:173], v[204:207], v[40:43]
	v_mfma_f32_16x16x32_bf16 v[28:31], v[154:157], v[212:215], v[28:31]
	v_mfma_f32_16x16x32_bf16 v[24:27], v[170:173], v[212:215], v[24:27]
	v_mfma_f32_16x16x32_bf16 v[12:15], v[154:157], v[220:223], v[12:15]
	v_mfma_f32_16x16x32_bf16 v[8:11], v[170:173], v[220:223], v[8:11]
	s_setprio 0
	s_setprio 1
	v_mfma_f32_16x16x32_bf16 v[52:55], v[174:177], v[190:193], v[52:55]
	v_mfma_f32_16x16x32_bf16 v[48:51], v[182:185], v[190:193], v[48:51]
	v_mfma_f32_16x16x32_bf16 v[36:39], v[174:177], v[200:203], v[36:39]
	v_mfma_f32_16x16x32_bf16 v[32:35], v[182:185], v[200:203], v[32:35]
	v_mfma_f32_16x16x32_bf16 v[20:23], v[174:177], v[208:211], v[20:23]
	v_mfma_f32_16x16x32_bf16 v[16:19], v[182:185], v[208:211], v[16:19]
	v_mfma_f32_16x16x32_bf16 v[4:7], v[174:177], v[216:219], v[4:7]
	v_mfma_f32_16x16x32_bf16 v[0:3], v[182:185], v[216:219], v[0:3]
	v_mfma_f32_16x16x32_bf16 v[52:55], v[178:181], v[196:199], v[52:55]
	v_mfma_f32_16x16x32_bf16 v[48:51], v[186:189], v[196:199], v[48:51]
	v_mfma_f32_16x16x32_bf16 v[36:39], v[178:181], v[204:207], v[36:39]
	v_mfma_f32_16x16x32_bf16 v[32:35], v[186:189], v[204:207], v[32:35]
	v_mfma_f32_16x16x32_bf16 v[20:23], v[178:181], v[212:215], v[20:23]
	v_mfma_f32_16x16x32_bf16 v[16:19], v[186:189], v[212:215], v[16:19]
	v_mfma_f32_16x16x32_bf16 v[4:7], v[178:181], v[220:223], v[4:7]
	v_mfma_f32_16x16x32_bf16 v[0:3], v[186:189], v[220:223], v[0:3]
	s_barrier
	s_setprio 0
	s_add_i32 s52, s52, 2
	s_add_u32 s34, s34, 0x100
	s_addc_u32 s35, s35, 0
	s_add_u32 s50, s50, 0x100
	s_addc_u32 s51, s51, 0
	s_cmp_gt_u32 s52, 13
	s_cbranch_scc0 .LBB0_521
	s_and_b64 vcc, exec, s[20:21]
	s_cbranch_vccz .LBB0_524
	s_barrier

; #define PG8_STAGE(bufoff, gbase, voff) do { _Pragma("unroll") for (int _i = 0; _i < 2; ++_i) \
;         __builtin_amdgcn_global_load_lds((const unsigned*)((const char*)(gbase) + (voff)[_i]), (PG8_LAS unsigned*)(lds + (bufoff) + ldsw + _i * 8192), 16, 0, 0); } while (0)
; #define PG8_LDA(dst, b, h) do { _Pragma("unroll") for (int m = 0; m < 4; ++m) _Pragma("unroll") for (int k = 0; k < 2; ++k) dst[m][k] = *(const PG8_LAS bf16x8*)(lds + PG8_SA(b, h) + aoff + m * 2048 + k * 1024); } while (0)
; #define PG8_LDB(dst, b, h) do { _Pragma("unroll") for (int n = 0; n < 2; ++n) _Pragma("unroll") for (int k = 0; k < 2; ++k) dst[n][k] = *(const PG8_LAS bf16x8*)(lds + PG8_SB(b, h) + boff + n * 2048 + k * 1024); } while (0)
; #define PG8_MMA(ai, bj, At, Bt) do { __builtin_amdgcn_s_setprio(1); _Pragma("unroll") for (int m = 0; m < 4; ++m) _Pragma("unroll") for (int n = 0; n < 2; ++n) _Pragma("unroll") for (int k = 0; k < 2; ++k) \
;         acc[ai][bj][m][n] = __builtin_amdgcn_mfma_f32_16x16x32_bf16(Bt[n][k], At[m][k], acc[ai][bj][m][n], 0, 0, 0); __builtin_amdgcn_s_setprio(0); } while (0)
; #define PG8_WAIT_V(n) asm volatile("s_waitcnt vmcnt(" #n ")" ::: "memory")
; #define PG8_WAIT_L(n) asm volatile("s_waitcnt lgkmcnt(" #n ")" ::: "memory")
; #define PG8_BAR __builtin_amdgcn_s_barrier()
; #define PG8_SCHED __builtin_amdgcn_sched_barrier(0)
; template <class Epi, class Sched, bool ALIGN_EPI = false, bool SP2 = false>
; __device__ __forceinline__ void gemm_phase(PG8_LAS unsigned char* lds, const Gemm g, const Sched& S, const Epi& E) {
;     ...
;             PG8_LDB(B0, 0, 0); PG8_LDB(B1, 0, 1); PG8_SCHED; PG8_LDA(At, 0, 0); PG8_STAGE(PG8_SA(1, 1), a1 + hstepA, voffA);
;             PG8_WAIT_V(8); PG8_WAIT_L(0); PG8_BAR; PG8_MMA(0, 0, At, B0); PG8_MMA(0, 1, At, B1); PG8_BAR; PG8_SCHED;
;             PG8_LDA(At, 0, 1); PG8_STAGE(PG8_SB(0, 0), b2, voffB); PG8_STAGE(PG8_SB(0, 1), b2 + hstepB, voffB); PG8_STAGE(PG8_SA(0, 0), a2, voffA);
;             PG8_WAIT_V(8); PG8_WAIT_L(0); PG8_BAR; PG8_MMA(1, 0, At, B0); PG8_MMA(1, 1, At, B1); PG8_BAR; PG8_SCHED;
.LBB0_541:
	ds_read_b128 v[144:147], v153
	ds_read_b128 v[156:159], v153 offset:1024
	ds_read_b128 v[170:173], v153 offset:2048
	ds_read_b128 v[174:177], v153 offset:3072
	ds_read_b128 v[178:181], v154
	ds_read_b128 v[182:185], v154 offset:1024
	ds_read_b128 v[186:189], v154 offset:2048
	ds_read_b128 v[190:193], v154 offset:3072
	s_add_u32 s40, s38, 0xfffc0080
	s_addc_u32 s41, s39, -1
	s_cmp_eq_u32 s60, 12
	s_cselect_b32 s43, s29, s41
	s_cselect_b32 s42, s52, s40
	s_cselect_b32 s41, s27, s55
	s_cselect_b32 s40, s53, s54
	v_lshl_add_u64 v[148:149], s[38:39], 0, v[136:137]
	s_add_i32 m0, s3, 0xc000
	ds_read_b128 v[196:199], v155
	ds_read_b128 v[200:203], v155 offset:1024
	ds_read_b128 v[204:207], v155 offset:2048
	ds_read_b128 v[208:211], v155 offset:3072
	ds_read_b128 v[212:215], v155 offset:4096
	ds_read_b128 v[216:219], v155 offset:5120
	ds_read_b128 v[220:223], v155 offset:6144
	ds_read_b128 v[224:227], v155 offset:7168
	global_load_lds_dwordx4 v[148:149], off
	v_lshl_add_u64 v[148:149], s[38:39], 0, v[138:139]
	s_add_i32 m0, s3, 0xe000
	s_nop 0
	global_load_lds_dwordx4 v[148:149], off
	s_waitcnt vmcnt(8)
	s_waitcnt lgkmcnt(0)
	s_setprio 1
	s_barrier
	v_mfma_f32_16x16x32_bf16 v[124:127], v[144:147], v[196:199], v[124:127]
	v_mfma_f32_16x16x32_bf16 v[120:123], v[170:173], v[196:199], v[120:123]
	v_mfma_f32_16x16x32_bf16 v[108:111], v[144:147], v[204:207], v[108:111]
	v_mfma_f32_16x16x32_bf16 v[104:107], v[170:173], v[204:207], v[104:107]
	v_mfma_f32_16x16x32_bf16 v[92:95], v[144:147], v[212:215], v[92:95]
	v_mfma_f32_16x16x32_bf16 v[88:91], v[170:173], v[212:215], v[88:91]
	v_mfma_f32_16x16x32_bf16 v[76:79], v[144:147], v[220:223], v[76:79]
	v_mfma_f32_16x16x32_bf16 v[72:75], v[170:173], v[220:223], v[72:75]
	v_mfma_f32_16x16x32_bf16 v[124:127], v[156:159], v[200:203], v[124:127]
	v_mfma_f32_16x16x32_bf16 v[120:123], v[174:177], v[200:203], v[120:123]
	v_mfma_f32_16x16x32_bf16 v[108:111], v[156:159], v[208:211], v[108:111]
	v_mfma_f32_16x16x32_bf16 v[104:107], v[174:177], v[208:211], v[104:107]
	v_mfma_f32_16x16x32_bf16 v[92:95], v[156:159], v[216:219], v[92:95]
	v_mfma_f32_16x16x32_bf16 v[88:91], v[174:177], v[216:219], v[88:91]
	v_mfma_f32_16x16x32_bf16 v[76:79], v[156:159], v[224:227], v[76:79]
	v_mfma_f32_16x16x32_bf16 v[72:75], v[174:177], v[224:227], v[72:75]
	s_setprio 0
	s_setprio 1
	v_mfma_f32_16x16x32_bf16 v[116:119], v[178:181], v[196:199], v[116:119]
	v_mfma_f32_16x16x32_bf16 v[112:115], v[186:189], v[196:199], v[112:115]
	v_mfma_f32_16x16x32_bf16 v[100:103], v[178:181], v[204:207], v[100:103]
	v_mfma_f32_16x16x32_bf16 v[96:99], v[186:189], v[204:207], v[96:99]
	v_mfma_f32_16x16x32_bf16 v[84:87], v[178:181], v[212:215], v[84:87]
	v_mfma_f32_16x16x32_bf16 v[80:83], v[186:189], v[212:215], v[80:83]
	v_mfma_f32_16x16x32_bf16 v[68:71], v[178:181], v[220:223], v[68:71]
	v_mfma_f32_16x16x32_bf16 v[64:67], v[186:189], v[220:223], v[64:67]
	v_mfma_f32_16x16x32_bf16 v[116:119], v[182:185], v[200:203], v[116:119]
	v_mfma_f32_16x16x32_bf16 v[112:115], v[190:193], v[200:203], v[112:115]
	v_mfma_f32_16x16x32_bf16 v[100:103], v[182:185], v[208:211], v[100:103]
	v_mfma_f32_16x16x32_bf16 v[96:99], v[190:193], v[208:211], v[96:99]
	v_mfma_f32_16x16x32_bf16 v[84:87], v[182:185], v[216:219], v[84:87]
	v_mfma_f32_16x16x32_bf16 v[80:83], v[190:193], v[216:219], v[80:83]
	v_mfma_f32_16x16x32_bf16 v[68:71], v[182:185], v[224:227], v[68:71]
	v_mfma_f32_16x16x32_bf16 v[64:67], v[190:193], v[224:227], v[64:67]
	s_barrier
	s_setprio 0
	s_add_i32 s61, s56, s0
	v_lshl_add_u64 v[148:149], s[40:41], 0, v[132:133]
	s_mov_b32 m0, s61
	ds_read_b128 v[196:199], v155 offset:16384
	ds_read_b128 v[200:203], v155 offset:17408
	ds_read_b128 v[204:207], v155 offset:18432
	ds_read_b128 v[208:211], v155 offset:19456
	ds_read_b128 v[212:215], v155 offset:20480
	ds_read_b128 v[216:219], v155 offset:21504
	ds_read_b128 v[220:223], v155 offset:22528
	ds_read_b128 v[224:227], v155 offset:23552
	global_load_lds_dwordx4 v[148:149], off
	s_add_i32 m0, s61, 0x2000
	s_add_u32 s62, s40, 0x40000
	v_lshl_add_u64 v[160:161], s[40:41], 0, v[128:129]
	s_addc_u32 s63, s41, 0
	s_add_i32 s61, s50, s0
	global_load_lds_dwordx4 v[160:161], off
	v_lshl_add_u64 v[228:229], s[62:63], 0, v[132:133]
	s_mov_b32 m0, s61
	v_lshl_add_u64 v[230:231], s[42:43], 0, v[130:131]
	global_load_lds_dwordx4 v[228:229], off
	v_lshl_add_u64 v[228:229], s[62:63], 0, v[128:129]
	s_add_i32 m0, s61, 0x2000
	s_nop 0
	global_load_lds_dwordx4 v[228:229], off
	v_lshl_add_u64 v[228:229], s[42:43], 0, v[134:135]
	s_mov_b32 m0, s3
	s_nop 0
	global_load_lds_dwordx4 v[228:229], off
	s_mov_b32 m0, s33
	s_nop 0
	global_load_lds_dwordx4 v[230:231], off
	s_waitcnt vmcnt(8)
	s_waitcnt lgkmcnt(0)
	s_setprio 1
	s_barrier
; #define PG8_STAGE(bufoff, gbase, voff) do { _Pragma("unroll") for (int _i = 0; _i < 2; ++_i) \
;         __builtin_amdgcn_global_load_lds((const unsigned*)((const char*)(gbase) + (voff)[_i]), (PG8_LAS unsigned*)(lds + (bufoff) + ldsw + _i * 8192), 16, 0, 0); } while (0)
; #define PG8_LDA(dst, b, h) do { _Pragma("unroll") for (int m = 0; m < 4; ++m) _Pragma("unroll") for (int k = 0; k < 2; ++k) dst[m][k] = *(const PG8_LAS bf16x8*)(lds + PG8_SA(b, h) + aoff + m * 2048 + k * 1024); } while (0)
; #define PG8_LDB(dst, b, h) do { _Pragma("unroll") for (int n = 0; n < 2; ++n) _Pragma("unroll") for (int k = 0; k < 2; ++k) dst[n][k] = *(const PG8_LAS bf16x8*)(lds + PG8_SB(b, h) + boff + n * 2048 + k * 1024); } while (0)
; #define PG8_MMA(ai, bj, At, Bt) do { __builtin_amdgcn_s_setprio(1); _Pragma("unroll") for (int m = 0; m < 4; ++m) _Pragma("unroll") for (int n = 0; n < 2; ++n) _Pragma("unroll") for (int k = 0; k < 2; ++k) \
;         acc[ai][bj][m][n] = __builtin_amdgcn_mfma_f32_16x16x32_bf16(Bt[n][k], At[m][k], acc[ai][bj][m][n], 0, 0, 0); __builtin_amdgcn_s_setprio(0); } while (0)
; #define PG8_WAIT_V(n) asm volatile("s_waitcnt vmcnt(" #n ")" ::: "memory")
; #define PG8_WAIT_L(n) asm volatile("s_waitcnt lgkmcnt(" #n ")" ::: "memory")
; #define PG8_BAR __builtin_amdgcn_s_barrier()
; #define PG8_SCHED __builtin_amdgcn_sched_barrier(0)
; template <class Epi, class Sched, bool ALIGN_EPI = false, bool SP2 = false>
; __device__ __forceinline__ void gemm_phase(PG8_LAS unsigned char* lds, const Gemm g, const Sched& S, const Epi& E) {
;     ...
;             PG8_WAIT_V(8); PG8_WAIT_L(0); PG8_BAR; PG8_MMA(1, 0, At, B0); PG8_MMA(1, 1, At, B1); PG8_BAR; PG8_SCHED;
;             PG8_LDB(B0, 1, 0); PG8_LDB(B1, 1, 1); PG8_SCHED; PG8_LDA(At, 1, 0); PG8_STAGE(PG8_SA(0, 1), a2 + hstepA, voffA);
;             PG8_WAIT_V(8); PG8_WAIT_L(0); PG8_BAR; PG8_MMA(0, 0, At, B0); PG8_MMA(0, 1, At, B1); PG8_BAR; PG8_SCHED;
	v_mfma_f32_16x16x32_bf16 v[60:63], v[144:147], v[196:199], v[60:63]
	v_mfma_f32_16x16x32_bf16 v[56:59], v[170:173], v[196:199], v[56:59]
	v_mfma_f32_16x16x32_bf16 v[44:47], v[144:147], v[204:207], v[44:47]
	v_mfma_f32_16x16x32_bf16 v[40:43], v[170:173], v[204:207], v[40:43]
	v_mfma_f32_16x16x32_bf16 v[28:31], v[144:147], v[212:215], v[28:31]
	v_mfma_f32_16x16x32_bf16 v[24:27], v[170:173], v[212:215], v[24:27]
	v_mfma_f32_16x16x32_bf16 v[12:15], v[144:147], v[220:223], v[12:15]
	v_mfma_f32_16x16x32_bf16 v[8:11], v[170:173], v[220:223], v[8:11]
	v_mfma_f32_16x16x32_bf16 v[60:63], v[156:159], v[200:203], v[60:63]
	v_mfma_f32_16x16x32_bf16 v[56:59], v[174:177], v[200:203], v[56:59]
	v_mfma_f32_16x16x32_bf16 v[44:47], v[156:159], v[208:211], v[44:47]
	v_mfma_f32_16x16x32_bf16 v[40:43], v[174:177], v[208:211], v[40:43]
	v_mfma_f32_16x16x32_bf16 v[28:31], v[156:159], v[216:219], v[28:31]
	v_mfma_f32_16x16x32_bf16 v[24:27], v[174:177], v[216:219], v[24:27]
	v_mfma_f32_16x16x32_bf16 v[12:15], v[156:159], v[224:227], v[12:15]
	v_mfma_f32_16x16x32_bf16 v[8:11], v[174:177], v[224:227], v[8:11]
	s_setprio 0
	s_setprio 1
	v_mfma_f32_16x16x32_bf16 v[52:55], v[178:181], v[196:199], v[52:55]
	v_mfma_f32_16x16x32_bf16 v[48:51], v[186:189], v[196:199], v[48:51]
	v_mfma_f32_16x16x32_bf16 v[36:39], v[178:181], v[204:207], v[36:39]
	v_mfma_f32_16x16x32_bf16 v[32:35], v[186:189], v[204:207], v[32:35]
	v_mfma_f32_16x16x32_bf16 v[20:23], v[178:181], v[212:215], v[20:23]
	v_mfma_f32_16x16x32_bf16 v[16:19], v[186:189], v[212:215], v[16:19]
	v_mfma_f32_16x16x32_bf16 v[4:7], v[178:181], v[220:223], v[4:7]
	v_mfma_f32_16x16x32_bf16 v[0:3], v[186:189], v[220:223], v[0:3]
	v_mfma_f32_16x16x32_bf16 v[52:55], v[182:185], v[200:203], v[52:55]
	v_mfma_f32_16x16x32_bf16 v[48:51], v[190:193], v[200:203], v[48:51]
	v_mfma_f32_16x16x32_bf16 v[36:39], v[182:185], v[208:211], v[36:39]
	v_mfma_f32_16x16x32_bf16 v[32:35], v[190:193], v[208:211], v[32:35]
	v_mfma_f32_16x16x32_bf16 v[20:23], v[182:185], v[216:219], v[20:23]
	v_mfma_f32_16x16x32_bf16 v[16:19], v[190:193], v[216:219], v[16:19]
	v_mfma_f32_16x16x32_bf16 v[4:7], v[182:185], v[224:227], v[4:7]
	v_mfma_f32_16x16x32_bf16 v[0:3], v[190:193], v[224:227], v[0:3]
	s_barrier
	s_setprio 0
	s_add_i32 s61, 0, 0x18000
	v_add_u32_e32 v169, s61, v151
	s_add_i32 s62, 0, 0x1c000
	ds_read_b128 v[144:147], v169
	ds_read_b128 v[156:159], v169 offset:1024
	ds_read_b128 v[170:173], v169 offset:2048
	ds_read_b128 v[174:177], v169 offset:3072
	v_add_u32_e32 v169, s62, v151
	ds_read_b128 v[178:181], v169
	ds_read_b128 v[182:185], v169 offset:1024
	ds_read_b128 v[186:189], v169 offset:2048
	ds_read_b128 v[190:193], v169 offset:3072
	s_add_u32 s42, s42, 0x40000
	s_addc_u32 s43, s43, 0
	s_mov_b32 m0, s37
	v_lshl_add_u64 v[232:233], s[42:43], 0, v[134:135]
	ds_read_b128 v[196:199], v155 offset:32768
	ds_read_b128 v[200:203], v155 offset:33792
	ds_read_b128 v[204:207], v155 offset:34816
	ds_read_b128 v[208:211], v155 offset:35840
	ds_read_b128 v[212:215], v155 offset:36864
	ds_read_b128 v[216:219], v155 offset:37888
	ds_read_b128 v[220:223], v155 offset:38912
	ds_read_b128 v[224:227], v155 offset:39936
	global_load_lds_dwordx4 v[232:233], off
	v_lshl_add_u64 v[232:233], s[42:43], 0, v[130:131]
	s_mov_b32 m0, s47
	s_nop 0
	global_load_lds_dwordx4 v[232:233], off
	s_waitcnt vmcnt(8)
	s_waitcnt lgkmcnt(0)
	s_setprio 1
	s_barrier
	v_mfma_f32_16x16x32_bf16 v[124:127], v[144:147], v[196:199], v[124:127]
	v_mfma_f32_16x16x32_bf16 v[120:123], v[170:173], v[196:199], v[120:123]
	v_mfma_f32_16x16x32_bf16 v[108:111], v[144:147], v[204:207], v[108:111]
	v_mfma_f32_16x16x32_bf16 v[104:107], v[170:173], v[204:207], v[104:107]
	v_mfma_f32_16x16x32_bf16 v[92:95], v[144:147], v[212:215], v[92:95]
	v_mfma_f32_16x16x32_bf16 v[88:91], v[170:173], v[212:215], v[88:91]
	v_mfma_f32_16x16x32_bf16 v[76:79], v[144:147], v[220:223], v[76:79]
	v_mfma_f32_16x16x32_bf16 v[72:75], v[170:173], v[220:223], v[72:75]
	v_mfma_f32_16x16x32_bf16 v[124:127], v[156:159], v[200:203], v[124:127]
	v_mfma_f32_16x16x32_bf16 v[120:123], v[174:177], v[200:203], v[120:123]
	v_mfma_f32_16x16x32_bf16 v[108:111], v[156:159], v[208:211], v[108:111]
	v_mfma_f32_16x16x32_bf16 v[104:107], v[174:177], v[208:211], v[104:107]
	v_mfma_f32_16x16x32_bf16 v[92:95], v[156:159], v[216:219], v[92:95]
	v_mfma_f32_16x16x32_bf16 v[88:91], v[174:177], v[216:219], v[88:91]
	v_mfma_f32_16x16x32_bf16 v[76:79], v[156:159], v[224:227], v[76:79]
	v_mfma_f32_16x16x32_bf16 v[72:75], v[174:177], v[224:227], v[72:75]
	s_setprio 0
	s_setprio 1
	v_mfma_f32_16x16x32_bf16 v[116:119], v[178:181], v[196:199], v[116:119]
	v_mfma_f32_16x16x32_bf16 v[112:115], v[186:189], v[196:199], v[112:115]
	v_mfma_f32_16x16x32_bf16 v[100:103], v[178:181], v[204:207], v[100:103]
	v_mfma_f32_16x16x32_bf16 v[96:99], v[186:189], v[204:207], v[96:99]
	v_mfma_f32_16x16x32_bf16 v[84:87], v[178:181], v[212:215], v[84:87]
	v_mfma_f32_16x16x32_bf16 v[80:83], v[186:189], v[212:215], v[80:83]
	v_mfma_f32_16x16x32_bf16 v[68:71], v[178:181], v[220:223], v[68:71]
	v_mfma_f32_16x16x32_bf16 v[64:67], v[186:189], v[220:223], v[64:67]
	v_mfma_f32_16x16x32_bf16 v[116:119], v[182:185], v[200:203], v[116:119]
	v_mfma_f32_16x16x32_bf16 v[112:115], v[190:193], v[200:203], v[112:115]
	v_mfma_f32_16x16x32_bf16 v[100:103], v[182:185], v[208:211], v[100:103]
	v_mfma_f32_16x16x32_bf16 v[96:99], v[190:193], v[208:211], v[96:99]
	v_mfma_f32_16x16x32_bf16 v[84:87], v[182:185], v[216:219], v[84:87]
	v_mfma_f32_16x16x32_bf16 v[80:83], v[190:193], v[216:219], v[80:83]
	v_mfma_f32_16x16x32_bf16 v[68:71], v[182:185], v[224:227], v[68:71]
	v_mfma_f32_16x16x32_bf16 v[64:67], v[190:193], v[224:227], v[64:67]
	s_barrier
; #define PG8_STAGE(bufoff, gbase, voff) do { _Pragma("unroll") for (int _i = 0; _i < 2; ++_i) \
;         __builtin_amdgcn_global_load_lds((const unsigned*)((const char*)(gbase) + (voff)[_i]), (PG8_LAS unsigned*)(lds + (bufoff) + ldsw + _i * 8192), 16, 0, 0); } while (0)
; #define PG8_LDA(dst, b, h) do { _Pragma("unroll") for (int m = 0; m < 4; ++m) _Pragma("unroll") for (int k = 0; k < 2; ++k) dst[m][k] = *(const PG8_LAS bf16x8*)(lds + PG8_SA(b, h) + aoff + m * 2048 + k * 1024); } while (0)
; #define PG8_MMA(ai, bj, At, Bt) do { __builtin_amdgcn_s_setprio(1); _Pragma("unroll") for (int m = 0; m < 4; ++m) _Pragma("unroll") for (int n = 0; n < 2; ++n) _Pragma("unroll") for (int k = 0; k < 2; ++k) \
;         acc[ai][bj][m][n] = __builtin_amdgcn_mfma_f32_16x16x32_bf16(Bt[n][k], At[m][k], acc[ai][bj][m][n], 0, 0, 0); __builtin_amdgcn_s_setprio(0); } while (0)
; #define PG8_WAIT_V(n) asm volatile("s_waitcnt vmcnt(" #n ")" ::: "memory")
; #define PG8_WAIT_L(n) asm volatile("s_waitcnt lgkmcnt(" #n ")" ::: "memory")
; #define PG8_BAR __builtin_amdgcn_s_barrier()
; #define PG8_SCHED __builtin_amdgcn_sched_barrier(0)
; template <class Epi, class Sched, bool ALIGN_EPI = false, bool SP2 = false>
; __device__ __forceinline__ void gemm_phase(PG8_LAS unsigned char* lds, const Gemm g, const Sched& S, const Epi& E) {
;     ...
;             PG8_LDA(At, 1, 1); PG8_STAGE(PG8_SB(1, 0), b3, voffB); PG8_STAGE(PG8_SB(1, 1), b3 + hstepB, voffB); PG8_STAGE(PG8_SA(1, 0), a3, voffA);
;             PG8_WAIT_V(8); PG8_WAIT_L(0); PG8_BAR; PG8_MMA(1, 0, At, B0); PG8_MMA(1, 1, At, B1); PG8_BAR; PG8_SCHED;
;     ...
;         if constexpr (ALIGN_EPI) { if (wr == 0) PG8_BAR; }
	s_setprio 0
	s_add_i32 s42, s61, s0
	v_lshl_add_u64 v[148:149], v[148:149], 0, s[20:21]
	s_mov_b32 m0, s42
	ds_read_b128 v[196:199], v155 offset:49152
	ds_read_b128 v[200:203], v155 offset:50176
	ds_read_b128 v[204:207], v155 offset:51200
	ds_read_b128 v[208:211], v155 offset:52224
	ds_read_b128 v[212:215], v155 offset:53248
	ds_read_b128 v[216:219], v155 offset:54272
	ds_read_b128 v[220:223], v155 offset:55296
	ds_read_b128 v[224:227], v155 offset:56320
	global_load_lds_dwordx4 v[148:149], off
	s_add_i32 m0, s42, 0x2000
	s_add_u32 s40, s40, 0x40080
	v_lshl_add_u64 v[148:149], v[160:161], 0, s[20:21]
	s_addc_u32 s41, s41, 0
	s_add_i32 s42, s62, s0
	global_load_lds_dwordx4 v[148:149], off
	v_lshl_add_u64 v[148:149], s[40:41], 0, v[132:133]
	s_mov_b32 m0, s42
	s_nop 0
	global_load_lds_dwordx4 v[148:149], off
	v_lshl_add_u64 v[148:149], s[40:41], 0, v[128:129]
	s_add_i32 m0, s42, 0x2000
	s_nop 0
	global_load_lds_dwordx4 v[148:149], off
	v_lshl_add_u64 v[148:149], v[228:229], 0, s[20:21]
	s_mov_b32 m0, s48
	s_nop 0
	global_load_lds_dwordx4 v[148:149], off
	v_lshl_add_u64 v[148:149], v[230:231], 0, s[20:21]
	s_mov_b32 m0, s49
	s_nop 0
	global_load_lds_dwordx4 v[148:149], off
	s_waitcnt vmcnt(8)
	s_waitcnt lgkmcnt(0)
	s_setprio 1
	s_barrier
	v_mfma_f32_16x16x32_bf16 v[60:63], v[144:147], v[196:199], v[60:63]
	v_mfma_f32_16x16x32_bf16 v[56:59], v[170:173], v[196:199], v[56:59]
	v_mfma_f32_16x16x32_bf16 v[44:47], v[144:147], v[204:207], v[44:47]
	v_mfma_f32_16x16x32_bf16 v[40:43], v[170:173], v[204:207], v[40:43]
	v_mfma_f32_16x16x32_bf16 v[28:31], v[144:147], v[212:215], v[28:31]
	v_mfma_f32_16x16x32_bf16 v[24:27], v[170:173], v[212:215], v[24:27]
	v_mfma_f32_16x16x32_bf16 v[12:15], v[144:147], v[220:223], v[12:15]
	v_mfma_f32_16x16x32_bf16 v[8:11], v[170:173], v[220:223], v[8:11]
	v_mfma_f32_16x16x32_bf16 v[60:63], v[156:159], v[200:203], v[60:63]
	v_mfma_f32_16x16x32_bf16 v[56:59], v[174:177], v[200:203], v[56:59]
	v_mfma_f32_16x16x32_bf16 v[44:47], v[156:159], v[208:211], v[44:47]
	v_mfma_f32_16x16x32_bf16 v[40:43], v[174:177], v[208:211], v[40:43]
	v_mfma_f32_16x16x32_bf16 v[28:31], v[156:159], v[216:219], v[28:31]
	v_mfma_f32_16x16x32_bf16 v[24:27], v[174:177], v[216:219], v[24:27]
	v_mfma_f32_16x16x32_bf16 v[12:15], v[156:159], v[224:227], v[12:15]
	v_mfma_f32_16x16x32_bf16 v[8:11], v[174:177], v[224:227], v[8:11]
	s_setprio 0
	s_setprio 1
	v_mfma_f32_16x16x32_bf16 v[52:55], v[178:181], v[196:199], v[52:55]
	v_mfma_f32_16x16x32_bf16 v[48:51], v[186:189], v[196:199], v[48:51]
	v_mfma_f32_16x16x32_bf16 v[36:39], v[178:181], v[204:207], v[36:39]
	v_mfma_f32_16x16x32_bf16 v[32:35], v[186:189], v[204:207], v[32:35]
	v_mfma_f32_16x16x32_bf16 v[20:23], v[178:181], v[212:215], v[20:23]
	v_mfma_f32_16x16x32_bf16 v[16:19], v[186:189], v[212:215], v[16:19]
	v_mfma_f32_16x16x32_bf16 v[4:7], v[178:181], v[220:223], v[4:7]
	v_mfma_f32_16x16x32_bf16 v[0:3], v[186:189], v[220:223], v[0:3]
	v_mfma_f32_16x16x32_bf16 v[52:55], v[182:185], v[200:203], v[52:55]
	v_mfma_f32_16x16x32_bf16 v[48:51], v[190:193], v[200:203], v[48:51]
	v_mfma_f32_16x16x32_bf16 v[36:39], v[182:185], v[208:211], v[36:39]
	v_mfma_f32_16x16x32_bf16 v[32:35], v[190:193], v[208:211], v[32:35]
	v_mfma_f32_16x16x32_bf16 v[20:23], v[182:185], v[216:219], v[20:23]
	v_mfma_f32_16x16x32_bf16 v[16:19], v[190:193], v[216:219], v[16:19]
	v_mfma_f32_16x16x32_bf16 v[4:7], v[182:185], v[224:227], v[4:7]
	v_mfma_f32_16x16x32_bf16 v[0:3], v[190:193], v[224:227], v[0:3]
	s_barrier
	s_setprio 0
	s_add_i32 s60, s60, 2
	s_add_u32 s38, s38, 0x100
	s_addc_u32 s39, s39, 0
	s_add_u32 s54, s54, 0x100
	s_addc_u32 s55, s55, 0
	s_cmp_gt_u32 s60, 13
	s_cbranch_scc0 .LBB0_541
	s_and_b64 vcc, exec, s[22:23]
	s_cbranch_vccz .LBB0_544
	s_barrier

; #define PG8_STAGE(bufoff, gbase, voff) do { _Pragma("unroll") for (int _i = 0; _i < 2; ++_i) \
;         __builtin_amdgcn_global_load_lds((const unsigned*)((const char*)(gbase) + (voff)[_i]), (PG8_LAS unsigned*)(lds + (bufoff) + ldsw + _i * 8192), 16, 0, 0); } while (0)
; #define PG8_LDA(dst, b, h) do { _Pragma("unroll") for (int m = 0; m < 4; ++m) _Pragma("unroll") for (int k = 0; k < 2; ++k) dst[m][k] = *(const PG8_LAS bf16x8*)(lds + PG8_SA(b, h) + aoff + m * 2048 + k * 1024); } while (0)
; #define PG8_LDB(dst, b, h) do { _Pragma("unroll") for (int n = 0; n < 2; ++n) _Pragma("unroll") for (int k = 0; k < 2; ++k) dst[n][k] = *(const PG8_LAS bf16x8*)(lds + PG8_SB(b, h) + boff + n * 2048 + k * 1024); } while (0)
; #define PG8_MMA(ai, bj, At, Bt) do { __builtin_amdgcn_s_setprio(1); _Pragma("unroll") for (int m = 0; m < 4; ++m) _Pragma("unroll") for (int n = 0; n < 2; ++n) _Pragma("unroll") for (int k = 0; k < 2; ++k) \
;         acc[ai][bj][m][n] = __builtin_amdgcn_mfma_f32_16x16x32_bf16(Bt[n][k], At[m][k], acc[ai][bj][m][n], 0, 0, 0); __builtin_amdgcn_s_setprio(0); } while (0)
; #define PG8_WAIT_V(n) asm volatile("s_waitcnt vmcnt(" #n ")" ::: "memory")
; #define PG8_WAIT_L(n) asm volatile("s_waitcnt lgkmcnt(" #n ")" ::: "memory")
; #define PG8_BAR __builtin_amdgcn_s_barrier()
; #define PG8_SCHED __builtin_amdgcn_sched_barrier(0)
; template <class Epi, class Sched, bool ALIGN_EPI = false, bool SP2 = false>
; __device__ __forceinline__ void gemm_phase(PG8_LAS unsigned char* lds, const Gemm g, const Sched& S, const Epi& E) {
;     ...
;             PG8_LDB(B0, 0, 0); PG8_LDB(B1, 0, 1); PG8_SCHED; PG8_LDA(At, 0, 0); PG8_STAGE(PG8_SA(1, 1), a1 + hstepA, voffA);
;             PG8_WAIT_V(8); PG8_WAIT_L(0); PG8_BAR; PG8_MMA(0, 0, At, B0); PG8_MMA(0, 1, At, B1); PG8_BAR; PG8_SCHED;
;             PG8_LDA(At, 0, 1); PG8_STAGE(PG8_SB(0, 0), b2, voffB); PG8_STAGE(PG8_SB(0, 1), b2 + hstepB, voffB); PG8_STAGE(PG8_SA(0, 0), a2, voffA);
;             PG8_WAIT_V(8); PG8_WAIT_L(0); PG8_BAR; PG8_MMA(1, 0, At, B0); PG8_MMA(1, 1, At, B1); PG8_BAR; PG8_SCHED;
.LBB0_613:
	ds_read_b128 v[128:131], v161
	ds_read_b128 v[132:135], v161 offset:1024
	ds_read_b128 v[136:139], v161 offset:2048
	ds_read_b128 v[140:143], v161 offset:3072
	ds_read_b128 v[172:175], v169
	ds_read_b128 v[176:179], v169 offset:1024
	ds_read_b128 v[180:183], v169 offset:2048
	ds_read_b128 v[184:187], v169 offset:3072
	s_add_u32 s42, s40, 0xfff80080
	s_addc_u32 s43, s41, -1
	s_cmp_eq_u32 s64, 28
	s_cselect_b32 s45, s31, s43
	s_cselect_b32 s44, s60, s42
	s_cselect_b32 s43, s29, s63
	s_cselect_b32 s42, s61, s62
	v_lshl_add_u64 v[156:157], s[40:41], 0, v[148:149]
	s_add_i32 m0, s39, 0xc000
	ds_read_b128 v[188:191], v170
	ds_read_b128 v[196:199], v170 offset:1024
	ds_read_b128 v[200:203], v170 offset:2048
	ds_read_b128 v[204:207], v170 offset:3072
	ds_read_b128 v[208:211], v170 offset:4096
	ds_read_b128 v[212:215], v170 offset:5120
	ds_read_b128 v[216:219], v170 offset:6144
	ds_read_b128 v[220:223], v170 offset:7168
	global_load_lds_dwordx4 v[156:157], off
	v_lshl_add_u64 v[156:157], s[40:41], 0, v[150:151]
	s_add_i32 m0, s39, 0xe000
	s_nop 0
	global_load_lds_dwordx4 v[156:157], off
	s_waitcnt vmcnt(8)
	s_waitcnt lgkmcnt(0)
	s_setprio 1
	s_barrier
	v_mfma_f32_16x16x32_bf16 v[124:127], v[128:131], v[188:191], v[124:127]
	v_mfma_f32_16x16x32_bf16 v[120:123], v[136:139], v[188:191], v[120:123]
	v_mfma_f32_16x16x32_bf16 v[112:115], v[128:131], v[200:203], v[112:115]
	v_mfma_f32_16x16x32_bf16 v[108:111], v[136:139], v[200:203], v[108:111]
	v_mfma_f32_16x16x32_bf16 v[96:99], v[128:131], v[208:211], v[96:99]
	v_mfma_f32_16x16x32_bf16 v[92:95], v[136:139], v[208:211], v[92:95]
	v_mfma_f32_16x16x32_bf16 v[80:83], v[128:131], v[216:219], v[80:83]
	v_mfma_f32_16x16x32_bf16 v[76:79], v[136:139], v[216:219], v[76:79]
	v_mfma_f32_16x16x32_bf16 v[124:127], v[132:135], v[196:199], v[124:127]
	v_mfma_f32_16x16x32_bf16 v[120:123], v[140:143], v[196:199], v[120:123]
	v_mfma_f32_16x16x32_bf16 v[112:115], v[132:135], v[204:207], v[112:115]
	v_mfma_f32_16x16x32_bf16 v[108:111], v[140:143], v[204:207], v[108:111]
	v_mfma_f32_16x16x32_bf16 v[96:99], v[132:135], v[212:215], v[96:99]
	v_mfma_f32_16x16x32_bf16 v[92:95], v[140:143], v[212:215], v[92:95]
	v_mfma_f32_16x16x32_bf16 v[80:83], v[132:135], v[220:223], v[80:83]
	v_mfma_f32_16x16x32_bf16 v[76:79], v[140:143], v[220:223], v[76:79]
	s_setprio 0
	s_setprio 1
	v_mfma_f32_16x16x32_bf16 v[116:119], v[172:175], v[188:191], v[116:119]
	v_mfma_f32_16x16x32_bf16 v[104:107], v[180:183], v[188:191], v[104:107]
	v_mfma_f32_16x16x32_bf16 v[100:103], v[172:175], v[200:203], v[100:103]
	v_mfma_f32_16x16x32_bf16 v[88:91], v[180:183], v[200:203], v[88:91]
	v_mfma_f32_16x16x32_bf16 v[84:87], v[172:175], v[208:211], v[84:87]
	v_mfma_f32_16x16x32_bf16 v[72:75], v[180:183], v[208:211], v[72:75]
	v_mfma_f32_16x16x32_bf16 v[68:71], v[172:175], v[216:219], v[68:71]
	v_mfma_f32_16x16x32_bf16 v[64:67], v[180:183], v[216:219], v[64:67]
	v_mfma_f32_16x16x32_bf16 v[116:119], v[176:179], v[196:199], v[116:119]
	v_mfma_f32_16x16x32_bf16 v[104:107], v[184:187], v[196:199], v[104:107]
	v_mfma_f32_16x16x32_bf16 v[100:103], v[176:179], v[204:207], v[100:103]
	v_mfma_f32_16x16x32_bf16 v[88:91], v[184:187], v[204:207], v[88:91]
	v_mfma_f32_16x16x32_bf16 v[84:87], v[176:179], v[212:215], v[84:87]
	v_mfma_f32_16x16x32_bf16 v[72:75], v[184:187], v[212:215], v[72:75]
	v_mfma_f32_16x16x32_bf16 v[68:71], v[176:179], v[220:223], v[68:71]
	v_mfma_f32_16x16x32_bf16 v[64:67], v[184:187], v[220:223], v[64:67]
	s_barrier
	s_setprio 0
	s_add_i32 s65, s56, s33
	v_lshl_add_u64 v[156:157], s[42:43], 0, v[146:147]
	s_mov_b32 m0, s65
	ds_read_b128 v[188:191], v170 offset:16384
	ds_read_b128 v[196:199], v170 offset:17408
	ds_read_b128 v[200:203], v170 offset:18432
	ds_read_b128 v[204:207], v170 offset:19456
	ds_read_b128 v[208:211], v170 offset:20480
	ds_read_b128 v[212:215], v170 offset:21504
	ds_read_b128 v[216:219], v170 offset:22528
	ds_read_b128 v[220:223], v170 offset:23552
	global_load_lds_dwordx4 v[156:157], off
	s_add_i32 m0, s65, 0x2000
	s_add_u32 s66, s42, 0x80000
	v_lshl_add_u64 v[192:193], s[42:43], 0, v[144:145]
	s_addc_u32 s67, s43, 0
	s_add_i32 s65, s54, s33
	global_load_lds_dwordx4 v[192:193], off
	v_lshl_add_u64 v[224:225], s[66:67], 0, v[146:147]
	s_mov_b32 m0, s65
	v_lshl_add_u64 v[226:227], s[44:45], 0, v[144:145]
	global_load_lds_dwordx4 v[224:225], off
	v_lshl_add_u64 v[224:225], s[66:67], 0, v[144:145]
	s_add_i32 m0, s65, 0x2000
	s_nop 0
	global_load_lds_dwordx4 v[224:225], off
	v_lshl_add_u64 v[224:225], s[44:45], 0, v[146:147]
	s_mov_b32 m0, s39
	s_nop 0
	global_load_lds_dwordx4 v[224:225], off
	s_mov_b32 m0, s46
	s_nop 0
	global_load_lds_dwordx4 v[226:227], off
	s_waitcnt vmcnt(8)
	s_waitcnt lgkmcnt(0)
	s_setprio 1
	s_barrier
; #define PG8_STAGE(bufoff, gbase, voff) do { _Pragma("unroll") for (int _i = 0; _i < 2; ++_i) \
;         __builtin_amdgcn_global_load_lds((const unsigned*)((const char*)(gbase) + (voff)[_i]), (PG8_LAS unsigned*)(lds + (bufoff) + ldsw + _i * 8192), 16, 0, 0); } while (0)
; #define PG8_LDA(dst, b, h) do { _Pragma("unroll") for (int m = 0; m < 4; ++m) _Pragma("unroll") for (int k = 0; k < 2; ++k) dst[m][k] = *(const PG8_LAS bf16x8*)(lds + PG8_SA(b, h) + aoff + m * 2048 + k * 1024); } while (0)
; #define PG8_LDB(dst, b, h) do { _Pragma("unroll") for (int n = 0; n < 2; ++n) _Pragma("unroll") for (int k = 0; k < 2; ++k) dst[n][k] = *(const PG8_LAS bf16x8*)(lds + PG8_SB(b, h) + boff + n * 2048 + k * 1024); } while (0)
; #define PG8_MMA(ai, bj, At, Bt) do { __builtin_amdgcn_s_setprio(1); _Pragma("unroll") for (int m = 0; m < 4; ++m) _Pragma("unroll") for (int n = 0; n < 2; ++n) _Pragma("unroll") for (int k = 0; k < 2; ++k) \
;         acc[ai][bj][m][n] = __builtin_amdgcn_mfma_f32_16x16x32_bf16(Bt[n][k], At[m][k], acc[ai][bj][m][n], 0, 0, 0); __builtin_amdgcn_s_setprio(0); } while (0)
; #define PG8_WAIT_V(n) asm volatile("s_waitcnt vmcnt(" #n ")" ::: "memory")
; #define PG8_WAIT_L(n) asm volatile("s_waitcnt lgkmcnt(" #n ")" ::: "memory")
; #define PG8_BAR __builtin_amdgcn_s_barrier()
; #define PG8_SCHED __builtin_amdgcn_sched_barrier(0)
; template <class Epi, class Sched, bool ALIGN_EPI = false, bool SP2 = false>
; __device__ __forceinline__ void gemm_phase(PG8_LAS unsigned char* lds, const Gemm g, const Sched& S, const Epi& E) {
;     ...
;             PG8_WAIT_V(8); PG8_WAIT_L(0); PG8_BAR; PG8_MMA(1, 0, At, B0); PG8_MMA(1, 1, At, B1); PG8_BAR; PG8_SCHED;
;             PG8_LDB(B0, 1, 0); PG8_LDB(B1, 1, 1); PG8_SCHED; PG8_LDA(At, 1, 0); PG8_STAGE(PG8_SA(0, 1), a2 + hstepA, voffA);
;             PG8_WAIT_V(8); PG8_WAIT_L(0); PG8_BAR; PG8_MMA(0, 0, At, B0); PG8_MMA(0, 1, At, B1); PG8_BAR; PG8_SCHED;
	v_mfma_f32_16x16x32_bf16 v[60:63], v[128:131], v[188:191], v[60:63]
	v_mfma_f32_16x16x32_bf16 v[56:59], v[136:139], v[188:191], v[56:59]
	v_mfma_f32_16x16x32_bf16 v[48:51], v[128:131], v[200:203], v[48:51]
	v_mfma_f32_16x16x32_bf16 v[44:47], v[136:139], v[200:203], v[44:47]
	v_mfma_f32_16x16x32_bf16 v[32:35], v[128:131], v[208:211], v[32:35]
	v_mfma_f32_16x16x32_bf16 v[28:31], v[136:139], v[208:211], v[28:31]
	v_mfma_f32_16x16x32_bf16 v[16:19], v[128:131], v[216:219], v[16:19]
	v_mfma_f32_16x16x32_bf16 v[12:15], v[136:139], v[216:219], v[12:15]
	v_mfma_f32_16x16x32_bf16 v[60:63], v[132:135], v[196:199], v[60:63]
	v_mfma_f32_16x16x32_bf16 v[56:59], v[140:143], v[196:199], v[56:59]
	v_mfma_f32_16x16x32_bf16 v[48:51], v[132:135], v[204:207], v[48:51]
	v_mfma_f32_16x16x32_bf16 v[44:47], v[140:143], v[204:207], v[44:47]
	v_mfma_f32_16x16x32_bf16 v[32:35], v[132:135], v[212:215], v[32:35]
	v_mfma_f32_16x16x32_bf16 v[28:31], v[140:143], v[212:215], v[28:31]
	v_mfma_f32_16x16x32_bf16 v[16:19], v[132:135], v[220:223], v[16:19]
	v_mfma_f32_16x16x32_bf16 v[12:15], v[140:143], v[220:223], v[12:15]
	s_setprio 0
	s_setprio 1
	v_mfma_f32_16x16x32_bf16 v[52:55], v[172:175], v[188:191], v[52:55]
	v_mfma_f32_16x16x32_bf16 v[40:43], v[180:183], v[188:191], v[40:43]
	v_mfma_f32_16x16x32_bf16 v[36:39], v[172:175], v[200:203], v[36:39]
	v_mfma_f32_16x16x32_bf16 v[24:27], v[180:183], v[200:203], v[24:27]
	v_mfma_f32_16x16x32_bf16 v[20:23], v[172:175], v[208:211], v[20:23]
	v_mfma_f32_16x16x32_bf16 v[8:11], v[180:183], v[208:211], v[8:11]
	v_mfma_f32_16x16x32_bf16 v[4:7], v[172:175], v[216:219], v[4:7]
	v_mfma_f32_16x16x32_bf16 v[0:3], v[180:183], v[216:219], v[0:3]
	v_mfma_f32_16x16x32_bf16 v[52:55], v[176:179], v[196:199], v[52:55]
	v_mfma_f32_16x16x32_bf16 v[40:43], v[184:187], v[196:199], v[40:43]
	v_mfma_f32_16x16x32_bf16 v[36:39], v[176:179], v[204:207], v[36:39]
	v_mfma_f32_16x16x32_bf16 v[24:27], v[184:187], v[204:207], v[24:27]
	v_mfma_f32_16x16x32_bf16 v[20:23], v[176:179], v[212:215], v[20:23]
	v_mfma_f32_16x16x32_bf16 v[8:11], v[184:187], v[212:215], v[8:11]
	v_mfma_f32_16x16x32_bf16 v[4:7], v[176:179], v[220:223], v[4:7]
	v_mfma_f32_16x16x32_bf16 v[0:3], v[184:187], v[220:223], v[0:3]
	s_barrier
	s_setprio 0
	s_add_i32 s65, 0, 0x18000
	s_add_i32 s66, 0, 0x1c000
	v_add_u32_e32 v140, s65, v159
	v_add_u32_e32 v171, s66, v159
	ds_read_b128 v[128:131], v140
	ds_read_b128 v[132:135], v140 offset:1024
	ds_read_b128 v[136:139], v140 offset:2048
	ds_read_b128 v[140:143], v140 offset:3072
	ds_read_b128 v[172:175], v171
	ds_read_b128 v[176:179], v171 offset:1024
	ds_read_b128 v[180:183], v171 offset:2048
	ds_read_b128 v[184:187], v171 offset:3072
	s_add_u32 s44, s44, 0x80000
	s_addc_u32 s45, s45, 0
	s_mov_b32 m0, s47
	v_lshl_add_u64 v[228:229], s[44:45], 0, v[146:147]
	ds_read_b128 v[188:191], v170 offset:32768
	ds_read_b128 v[196:199], v170 offset:33792
	ds_read_b128 v[200:203], v170 offset:34816
	ds_read_b128 v[204:207], v170 offset:35840
	ds_read_b128 v[208:211], v170 offset:36864
	ds_read_b128 v[212:215], v170 offset:37888
	ds_read_b128 v[216:219], v170 offset:38912
	ds_read_b128 v[220:223], v170 offset:39936
	global_load_lds_dwordx4 v[228:229], off
	v_lshl_add_u64 v[228:229], s[44:45], 0, v[144:145]
	s_mov_b32 m0, s48
	s_nop 0
	global_load_lds_dwordx4 v[228:229], off
	s_waitcnt vmcnt(8)
	s_waitcnt lgkmcnt(0)
	s_setprio 1
	s_barrier
	v_mfma_f32_16x16x32_bf16 v[124:127], v[128:131], v[188:191], v[124:127]
	v_mfma_f32_16x16x32_bf16 v[120:123], v[136:139], v[188:191], v[120:123]
	v_mfma_f32_16x16x32_bf16 v[112:115], v[128:131], v[200:203], v[112:115]
	v_mfma_f32_16x16x32_bf16 v[108:111], v[136:139], v[200:203], v[108:111]
	v_mfma_f32_16x16x32_bf16 v[96:99], v[128:131], v[208:211], v[96:99]
	v_mfma_f32_16x16x32_bf16 v[92:95], v[136:139], v[208:211], v[92:95]
	v_mfma_f32_16x16x32_bf16 v[80:83], v[128:131], v[216:219], v[80:83]
	v_mfma_f32_16x16x32_bf16 v[76:79], v[136:139], v[216:219], v[76:79]
	v_mfma_f32_16x16x32_bf16 v[124:127], v[132:135], v[196:199], v[124:127]
	v_mfma_f32_16x16x32_bf16 v[120:123], v[140:143], v[196:199], v[120:123]
	v_mfma_f32_16x16x32_bf16 v[112:115], v[132:135], v[204:207], v[112:115]
	v_mfma_f32_16x16x32_bf16 v[108:111], v[140:143], v[204:207], v[108:111]
	v_mfma_f32_16x16x32_bf16 v[96:99], v[132:135], v[212:215], v[96:99]
	v_mfma_f32_16x16x32_bf16 v[92:95], v[140:143], v[212:215], v[92:95]
	v_mfma_f32_16x16x32_bf16 v[80:83], v[132:135], v[220:223], v[80:83]
	v_mfma_f32_16x16x32_bf16 v[76:79], v[140:143], v[220:223], v[76:79]
	s_setprio 0
	s_setprio 1
	v_mfma_f32_16x16x32_bf16 v[116:119], v[172:175], v[188:191], v[116:119]
	v_mfma_f32_16x16x32_bf16 v[104:107], v[180:183], v[188:191], v[104:107]
	v_mfma_f32_16x16x32_bf16 v[100:103], v[172:175], v[200:203], v[100:103]
	v_mfma_f32_16x16x32_bf16 v[88:91], v[180:183], v[200:203], v[88:91]
	v_mfma_f32_16x16x32_bf16 v[84:87], v[172:175], v[208:211], v[84:87]
	v_mfma_f32_16x16x32_bf16 v[72:75], v[180:183], v[208:211], v[72:75]
	v_mfma_f32_16x16x32_bf16 v[68:71], v[172:175], v[216:219], v[68:71]
	v_mfma_f32_16x16x32_bf16 v[64:67], v[180:183], v[216:219], v[64:67]
	v_mfma_f32_16x16x32_bf16 v[116:119], v[176:179], v[196:199], v[116:119]
	v_mfma_f32_16x16x32_bf16 v[104:107], v[184:187], v[196:199], v[104:107]
	v_mfma_f32_16x16x32_bf16 v[100:103], v[176:179], v[204:207], v[100:103]
	v_mfma_f32_16x16x32_bf16 v[88:91], v[184:187], v[204:207], v[88:91]
	v_mfma_f32_16x16x32_bf16 v[84:87], v[176:179], v[212:215], v[84:87]
	v_mfma_f32_16x16x32_bf16 v[72:75], v[184:187], v[212:215], v[72:75]
	v_mfma_f32_16x16x32_bf16 v[68:71], v[176:179], v[220:223], v[68:71]
	v_mfma_f32_16x16x32_bf16 v[64:67], v[184:187], v[220:223], v[64:67]
	s_barrier
; #define PG8_STAGE(bufoff, gbase, voff) do { _Pragma("unroll") for (int _i = 0; _i < 2; ++_i) \
;         __builtin_amdgcn_global_load_lds((const unsigned*)((const char*)(gbase) + (voff)[_i]), (PG8_LAS unsigned*)(lds + (bufoff) + ldsw + _i * 8192), 16, 0, 0); } while (0)
; #define PG8_LDA(dst, b, h) do { _Pragma("unroll") for (int m = 0; m < 4; ++m) _Pragma("unroll") for (int k = 0; k < 2; ++k) dst[m][k] = *(const PG8_LAS bf16x8*)(lds + PG8_SA(b, h) + aoff + m * 2048 + k * 1024); } while (0)
; #define PG8_MMA(ai, bj, At, Bt) do { __builtin_amdgcn_s_setprio(1); _Pragma("unroll") for (int m = 0; m < 4; ++m) _Pragma("unroll") for (int n = 0; n < 2; ++n) _Pragma("unroll") for (int k = 0; k < 2; ++k) \
;         acc[ai][bj][m][n] = __builtin_amdgcn_mfma_f32_16x16x32_bf16(Bt[n][k], At[m][k], acc[ai][bj][m][n], 0, 0, 0); __builtin_amdgcn_s_setprio(0); } while (0)
; #define PG8_WAIT_V(n) asm volatile("s_waitcnt vmcnt(" #n ")" ::: "memory")
; #define PG8_WAIT_L(n) asm volatile("s_waitcnt lgkmcnt(" #n ")" ::: "memory")
; #define PG8_BAR __builtin_amdgcn_s_barrier()
; #define PG8_SCHED __builtin_amdgcn_sched_barrier(0)
; template <class Epi, class Sched, bool ALIGN_EPI = false, bool SP2 = false>
; __device__ __forceinline__ void gemm_phase(PG8_LAS unsigned char* lds, const Gemm g, const Sched& S, const Epi& E) {
;     ...
;             PG8_LDA(At, 1, 1); PG8_STAGE(PG8_SB(1, 0), b3, voffB); PG8_STAGE(PG8_SB(1, 1), b3 + hstepB, voffB); PG8_STAGE(PG8_SA(1, 0), a3, voffA);
;             PG8_WAIT_V(8); PG8_WAIT_L(0); PG8_BAR; PG8_MMA(1, 0, At, B0); PG8_MMA(1, 1, At, B1); PG8_BAR; PG8_SCHED;
;     ...
;         if constexpr (ALIGN_EPI) { if (wr == 0) PG8_BAR; }
	s_setprio 0
	s_add_i32 s44, s65, s33
	v_lshl_add_u64 v[156:157], v[156:157], 0, s[10:11]
	s_mov_b32 m0, s44
	ds_read_b128 v[188:191], v170 offset:49152
	ds_read_b128 v[196:199], v170 offset:50176
	ds_read_b128 v[200:203], v170 offset:51200
	ds_read_b128 v[204:207], v170 offset:52224
	ds_read_b128 v[208:211], v170 offset:53248
	ds_read_b128 v[212:215], v170 offset:54272
	ds_read_b128 v[216:219], v170 offset:55296
	ds_read_b128 v[220:223], v170 offset:56320
	global_load_lds_dwordx4 v[156:157], off
	s_add_i32 m0, s44, 0x2000
	s_add_u32 s42, s42, 0x80080
	v_lshl_add_u64 v[156:157], v[192:193], 0, s[10:11]
	s_addc_u32 s43, s43, 0
	s_add_i32 s44, s66, s33
	global_load_lds_dwordx4 v[156:157], off
	v_lshl_add_u64 v[156:157], s[42:43], 0, v[146:147]
	s_mov_b32 m0, s44
	s_nop 0
	global_load_lds_dwordx4 v[156:157], off
	v_lshl_add_u64 v[156:157], s[42:43], 0, v[144:145]
	s_add_i32 m0, s44, 0x2000
	s_nop 0
	global_load_lds_dwordx4 v[156:157], off
	v_lshl_add_u64 v[156:157], v[224:225], 0, s[10:11]
	s_mov_b32 m0, s52
	s_nop 0
	global_load_lds_dwordx4 v[156:157], off
	v_lshl_add_u64 v[156:157], v[226:227], 0, s[10:11]
	s_mov_b32 m0, s53
	s_nop 0
	global_load_lds_dwordx4 v[156:157], off
	s_waitcnt vmcnt(8)
	s_waitcnt lgkmcnt(0)
	s_setprio 1
	s_barrier
	v_mfma_f32_16x16x32_bf16 v[60:63], v[128:131], v[188:191], v[60:63]
	v_mfma_f32_16x16x32_bf16 v[56:59], v[136:139], v[188:191], v[56:59]
	v_mfma_f32_16x16x32_bf16 v[48:51], v[128:131], v[200:203], v[48:51]
	v_mfma_f32_16x16x32_bf16 v[44:47], v[136:139], v[200:203], v[44:47]
	v_mfma_f32_16x16x32_bf16 v[32:35], v[128:131], v[208:211], v[32:35]
	v_mfma_f32_16x16x32_bf16 v[28:31], v[136:139], v[208:211], v[28:31]
	v_mfma_f32_16x16x32_bf16 v[16:19], v[128:131], v[216:219], v[16:19]
	v_mfma_f32_16x16x32_bf16 v[12:15], v[136:139], v[216:219], v[12:15]
	v_mfma_f32_16x16x32_bf16 v[60:63], v[132:135], v[196:199], v[60:63]
	v_mfma_f32_16x16x32_bf16 v[56:59], v[140:143], v[196:199], v[56:59]
	v_mfma_f32_16x16x32_bf16 v[48:51], v[132:135], v[204:207], v[48:51]
	v_mfma_f32_16x16x32_bf16 v[44:47], v[140:143], v[204:207], v[44:47]
	v_mfma_f32_16x16x32_bf16 v[32:35], v[132:135], v[212:215], v[32:35]
	v_mfma_f32_16x16x32_bf16 v[28:31], v[140:143], v[212:215], v[28:31]
	v_mfma_f32_16x16x32_bf16 v[16:19], v[132:135], v[220:223], v[16:19]
	v_mfma_f32_16x16x32_bf16 v[12:15], v[140:143], v[220:223], v[12:15]
	s_setprio 0
	s_setprio 1
	v_mfma_f32_16x16x32_bf16 v[52:55], v[172:175], v[188:191], v[52:55]
	v_mfma_f32_16x16x32_bf16 v[40:43], v[180:183], v[188:191], v[40:43]
	v_mfma_f32_16x16x32_bf16 v[36:39], v[172:175], v[200:203], v[36:39]
	v_mfma_f32_16x16x32_bf16 v[24:27], v[180:183], v[200:203], v[24:27]
	v_mfma_f32_16x16x32_bf16 v[20:23], v[172:175], v[208:211], v[20:23]
	v_mfma_f32_16x16x32_bf16 v[8:11], v[180:183], v[208:211], v[8:11]
	v_mfma_f32_16x16x32_bf16 v[4:7], v[172:175], v[216:219], v[4:7]
	v_mfma_f32_16x16x32_bf16 v[0:3], v[180:183], v[216:219], v[0:3]
	v_mfma_f32_16x16x32_bf16 v[52:55], v[176:179], v[196:199], v[52:55]
	v_mfma_f32_16x16x32_bf16 v[40:43], v[184:187], v[196:199], v[40:43]
	v_mfma_f32_16x16x32_bf16 v[36:39], v[176:179], v[204:207], v[36:39]
	v_mfma_f32_16x16x32_bf16 v[24:27], v[184:187], v[204:207], v[24:27]
	v_mfma_f32_16x16x32_bf16 v[20:23], v[176:179], v[212:215], v[20:23]
	v_mfma_f32_16x16x32_bf16 v[8:11], v[184:187], v[212:215], v[8:11]
	v_mfma_f32_16x16x32_bf16 v[4:7], v[176:179], v[220:223], v[4:7]
	v_mfma_f32_16x16x32_bf16 v[0:3], v[184:187], v[220:223], v[0:3]
	s_barrier
	s_setprio 0
	s_add_i32 s64, s64, 2
	s_add_u32 s40, s40, 0x100
	s_addc_u32 s41, s41, 0
	s_add_u32 s62, s62, 0x100
	s_addc_u32 s63, s63, 0
	s_cmp_gt_u32 s64, 29
	s_cbranch_scc0 .LBB0_613
	s_and_b64 vcc, exec, s[18:19]
	s_cbranch_vccz .LBB0_616
	s_barrier

; #define PG8_STAGE(bufoff, gbase, voff) do { _Pragma("unroll") for (int _i = 0; _i < 2; ++_i) \
;         __builtin_amdgcn_global_load_lds((const unsigned*)((const char*)(gbase) + (voff)[_i]), (PG8_LAS unsigned*)(lds + (bufoff) + ldsw + _i * 8192), 16, 0, 0); } while (0)
; #define PG8_LDA(dst, b, h) do { _Pragma("unroll") for (int m = 0; m < 4; ++m) _Pragma("unroll") for (int k = 0; k < 2; ++k) dst[m][k] = *(const PG8_LAS bf16x8*)(lds + PG8_SA(b, h) + aoff + m * 2048 + k * 1024); } while (0)
; #define PG8_LDB(dst, b, h) do { _Pragma("unroll") for (int n = 0; n < 2; ++n) _Pragma("unroll") for (int k = 0; k < 2; ++k) dst[n][k] = *(const PG8_LAS bf16x8*)(lds + PG8_SB(b, h) + boff + n * 2048 + k * 1024); } while (0)
; #define PG8_MMA(ai, bj, At, Bt) do { __builtin_amdgcn_s_setprio(1); _Pragma("unroll") for (int m = 0; m < 4; ++m) _Pragma("unroll") for (int n = 0; n < 2; ++n) _Pragma("unroll") for (int k = 0; k < 2; ++k) \
;         acc[ai][bj][m][n] = __builtin_amdgcn_mfma_f32_16x16x32_bf16(Bt[n][k], At[m][k], acc[ai][bj][m][n], 0, 0, 0); __builtin_amdgcn_s_setprio(0); } while (0)
; #define PG8_WAIT_V(n) asm volatile("s_waitcnt vmcnt(" #n ")" ::: "memory")
; #define PG8_WAIT_L(n) asm volatile("s_waitcnt lgkmcnt(" #n ")" ::: "memory")
; #define PG8_BAR __builtin_amdgcn_s_barrier()
; #define PG8_SCHED __builtin_amdgcn_sched_barrier(0)
; template <class Epi, class Sched, bool ALIGN_EPI = false, bool SP2 = false>
; __device__ __forceinline__ void gemm_phase(PG8_LAS unsigned char* lds, const Gemm g, const Sched& S, const Epi& E) {
;     ...
;             PG8_LDB(B0, 0, 0); PG8_LDB(B1, 0, 1); PG8_SCHED; PG8_LDA(At, 0, 0); PG8_STAGE(PG8_SA(1, 1), a1 + hstepA, voffA);
;             PG8_WAIT_V(8); PG8_WAIT_L(0); PG8_BAR; PG8_MMA(0, 0, At, B0); PG8_MMA(0, 1, At, B1); PG8_BAR; PG8_SCHED;
;             PG8_LDA(At, 0, 1); PG8_STAGE(PG8_SB(0, 0), b2, voffB); PG8_STAGE(PG8_SB(0, 1), b2 + hstepB, voffB); PG8_STAGE(PG8_SA(0, 0), a2, voffA);
;             PG8_WAIT_V(8); PG8_WAIT_L(0); PG8_BAR; PG8_MMA(1, 0, At, B0); PG8_MMA(1, 1, At, B1); PG8_BAR; PG8_SCHED;
.LBB0_736:
	s_add_u32 s34, s65, s30
	s_addc_u32 s35, s66, s31
	s_add_u32 s34, s34, 0x5b00100
	s_addc_u32 s35, s35, 0
	s_add_u32 s70, s67, s30
	s_addc_u32 s71, s68, s31
	s_cmpk_eq_i32 s30, 0xf00
	s_cselect_b32 s37, s29, s35
	s_cselect_b32 s36, s28, s34
	v_add_u32_e32 v169, s56, v148
	s_cselect_b32 s35, s5, s71
	s_cselect_b32 s34, s4, s70
	s_add_i32 s72, 0, 0x14000
	ds_read_b128 v[150:153], v169
	ds_read_b128 v[154:157], v169 offset:1024
	ds_read_b128 v[158:161], v169 offset:2048
	ds_read_b128 v[170:173], v169 offset:3072
	v_add_u32_e32 v169, s72, v148
	ds_read_b128 v[174:177], v169
	ds_read_b128 v[178:181], v169 offset:1024
	ds_read_b128 v[182:185], v169 offset:2048
	ds_read_b128 v[186:189], v169 offset:3072
	v_lshl_add_u64 v[224:225], v[140:141], 0, s[30:31]
	s_add_i32 m0, s3, 0xc000
	ds_read_b128 v[190:193], v149
	ds_read_b128 v[196:199], v149 offset:1024
	ds_read_b128 v[200:203], v149 offset:2048
	ds_read_b128 v[204:207], v149 offset:3072
	ds_read_b128 v[208:211], v149 offset:4096
	ds_read_b128 v[212:215], v149 offset:5120
	ds_read_b128 v[216:219], v149 offset:6144
	ds_read_b128 v[220:223], v149 offset:7168
	global_load_lds_dwordx4 v[224:225], off
	v_lshl_add_u64 v[224:225], v[142:143], 0, s[30:31]
	s_add_i32 m0, s3, 0xe000
	s_nop 0
	global_load_lds_dwordx4 v[224:225], off
	s_waitcnt vmcnt(8)
	s_waitcnt lgkmcnt(0)
	s_setprio 1
	s_barrier
	v_mfma_f32_16x16x32_bf16 v[124:127], v[150:153], v[190:193], v[124:127]
	v_mfma_f32_16x16x32_bf16 v[120:123], v[158:161], v[190:193], v[120:123]
	v_mfma_f32_16x16x32_bf16 v[116:119], v[150:153], v[200:203], v[116:119]
	v_mfma_f32_16x16x32_bf16 v[112:115], v[158:161], v[200:203], v[112:115]
	v_mfma_f32_16x16x32_bf16 v[100:103], v[150:153], v[208:211], v[100:103]
	v_mfma_f32_16x16x32_bf16 v[96:99], v[158:161], v[208:211], v[96:99]
	v_mfma_f32_16x16x32_bf16 v[84:87], v[150:153], v[216:219], v[84:87]
	v_mfma_f32_16x16x32_bf16 v[80:83], v[158:161], v[216:219], v[80:83]
	v_mfma_f32_16x16x32_bf16 v[124:127], v[154:157], v[196:199], v[124:127]
	v_mfma_f32_16x16x32_bf16 v[120:123], v[170:173], v[196:199], v[120:123]
	v_mfma_f32_16x16x32_bf16 v[116:119], v[154:157], v[204:207], v[116:119]
	v_mfma_f32_16x16x32_bf16 v[112:115], v[170:173], v[204:207], v[112:115]
	v_mfma_f32_16x16x32_bf16 v[100:103], v[154:157], v[212:215], v[100:103]
	v_mfma_f32_16x16x32_bf16 v[96:99], v[170:173], v[212:215], v[96:99]
	v_mfma_f32_16x16x32_bf16 v[84:87], v[154:157], v[220:223], v[84:87]
	v_mfma_f32_16x16x32_bf16 v[80:83], v[170:173], v[220:223], v[80:83]
	s_setprio 0
	s_setprio 1
	v_mfma_f32_16x16x32_bf16 v[108:111], v[174:177], v[190:193], v[108:111]
	v_mfma_f32_16x16x32_bf16 v[104:107], v[182:185], v[190:193], v[104:107]
	v_mfma_f32_16x16x32_bf16 v[92:95], v[174:177], v[200:203], v[92:95]
	v_mfma_f32_16x16x32_bf16 v[88:91], v[182:185], v[200:203], v[88:91]
	v_mfma_f32_16x16x32_bf16 v[76:79], v[174:177], v[208:211], v[76:79]
	v_mfma_f32_16x16x32_bf16 v[72:75], v[182:185], v[208:211], v[72:75]
	v_mfma_f32_16x16x32_bf16 v[68:71], v[174:177], v[216:219], v[68:71]
	v_mfma_f32_16x16x32_bf16 v[64:67], v[182:185], v[216:219], v[64:67]
	v_mfma_f32_16x16x32_bf16 v[108:111], v[178:181], v[196:199], v[108:111]
	v_mfma_f32_16x16x32_bf16 v[104:107], v[186:189], v[196:199], v[104:107]
	v_mfma_f32_16x16x32_bf16 v[92:95], v[178:181], v[204:207], v[92:95]
	v_mfma_f32_16x16x32_bf16 v[88:91], v[186:189], v[204:207], v[88:91]
	v_mfma_f32_16x16x32_bf16 v[76:79], v[178:181], v[212:215], v[76:79]
	v_mfma_f32_16x16x32_bf16 v[72:75], v[186:189], v[212:215], v[72:75]
	v_mfma_f32_16x16x32_bf16 v[68:71], v[178:181], v[220:223], v[68:71]
	v_mfma_f32_16x16x32_bf16 v[64:67], v[186:189], v[220:223], v[64:67]
	s_barrier
	s_setprio 0
	s_add_i32 s70, s56, s2
	v_lshl_add_u64 v[224:225], s[34:35], 0, v[132:133]
	s_mov_b32 m0, s70
	ds_read_b128 v[190:193], v149 offset:16384
	ds_read_b128 v[196:199], v149 offset:17408
	ds_read_b128 v[200:203], v149 offset:18432
	ds_read_b128 v[204:207], v149 offset:19456
	ds_read_b128 v[208:211], v149 offset:20480
	ds_read_b128 v[212:215], v149 offset:21504
	ds_read_b128 v[216:219], v149 offset:22528
	ds_read_b128 v[220:223], v149 offset:23552
	global_load_lds_dwordx4 v[224:225], off
	s_add_i32 m0, s70, 0x2000
	s_add_u32 s70, s34, 0x80000
	v_lshl_add_u64 v[226:227], s[34:35], 0, v[138:139]
	s_addc_u32 s71, s35, 0
	s_add_i32 s72, s72, s2
	global_load_lds_dwordx4 v[226:227], off
	v_lshl_add_u64 v[228:229], s[70:71], 0, v[132:133]
	s_mov_b32 m0, s72
	v_lshl_add_u64 v[230:231], s[36:37], 0, v[136:137]
	global_load_lds_dwordx4 v[228:229], off
	v_lshl_add_u64 v[228:229], s[70:71], 0, v[138:139]
	s_add_i32 m0, s72, 0x2000
	s_nop 0
	global_load_lds_dwordx4 v[228:229], off
	v_lshl_add_u64 v[228:229], s[36:37], 0, v[134:135]
	s_mov_b32 m0, s3
	s_nop 0
	global_load_lds_dwordx4 v[228:229], off
	s_mov_b32 m0, s26
	s_nop 0
	global_load_lds_dwordx4 v[230:231], off
	s_waitcnt vmcnt(8)
	s_waitcnt lgkmcnt(0)
	s_setprio 1
	s_barrier
; #define PG8_STAGE(bufoff, gbase, voff) do { _Pragma("unroll") for (int _i = 0; _i < 2; ++_i) \
;         __builtin_amdgcn_global_load_lds((const unsigned*)((const char*)(gbase) + (voff)[_i]), (PG8_LAS unsigned*)(lds + (bufoff) + ldsw + _i * 8192), 16, 0, 0); } while (0)
; #define PG8_LDA(dst, b, h) do { _Pragma("unroll") for (int m = 0; m < 4; ++m) _Pragma("unroll") for (int k = 0; k < 2; ++k) dst[m][k] = *(const PG8_LAS bf16x8*)(lds + PG8_SA(b, h) + aoff + m * 2048 + k * 1024); } while (0)
; #define PG8_LDB(dst, b, h) do { _Pragma("unroll") for (int n = 0; n < 2; ++n) _Pragma("unroll") for (int k = 0; k < 2; ++k) dst[n][k] = *(const PG8_LAS bf16x8*)(lds + PG8_SB(b, h) + boff + n * 2048 + k * 1024); } while (0)
; #define PG8_MMA(ai, bj, At, Bt) do { __builtin_amdgcn_s_setprio(1); _Pragma("unroll") for (int m = 0; m < 4; ++m) _Pragma("unroll") for (int n = 0; n < 2; ++n) _Pragma("unroll") for (int k = 0; k < 2; ++k) \
;         acc[ai][bj][m][n] = __builtin_amdgcn_mfma_f32_16x16x32_bf16(Bt[n][k], At[m][k], acc[ai][bj][m][n], 0, 0, 0); __builtin_amdgcn_s_setprio(0); } while (0)
; #define PG8_WAIT_V(n) asm volatile("s_waitcnt vmcnt(" #n ")" ::: "memory")
; #define PG8_WAIT_L(n) asm volatile("s_waitcnt lgkmcnt(" #n ")" ::: "memory")
; #define PG8_BAR __builtin_amdgcn_s_barrier()
; #define PG8_SCHED __builtin_amdgcn_sched_barrier(0)
; template <class Epi, class Sched, bool ALIGN_EPI = false, bool SP2 = false>
; __device__ __forceinline__ void gemm_phase(PG8_LAS unsigned char* lds, const Gemm g, const Sched& S, const Epi& E) {
;     ...
;             PG8_WAIT_V(8); PG8_WAIT_L(0); PG8_BAR; PG8_MMA(1, 0, At, B0); PG8_MMA(1, 1, At, B1); PG8_BAR; PG8_SCHED;
;             PG8_LDB(B0, 1, 0); PG8_LDB(B1, 1, 1); PG8_SCHED; PG8_LDA(At, 1, 0); PG8_STAGE(PG8_SA(0, 1), a2 + hstepA, voffA);
;             PG8_WAIT_V(8); PG8_WAIT_L(0); PG8_BAR; PG8_MMA(0, 0, At, B0); PG8_MMA(0, 1, At, B1); PG8_BAR; PG8_SCHED;
	v_mfma_f32_16x16x32_bf16 v[60:63], v[150:153], v[190:193], v[60:63]
	v_mfma_f32_16x16x32_bf16 v[56:59], v[158:161], v[190:193], v[56:59]
	v_mfma_f32_16x16x32_bf16 v[52:55], v[150:153], v[200:203], v[52:55]
	v_mfma_f32_16x16x32_bf16 v[48:51], v[158:161], v[200:203], v[48:51]
	v_mfma_f32_16x16x32_bf16 v[36:39], v[150:153], v[208:211], v[36:39]
	v_mfma_f32_16x16x32_bf16 v[32:35], v[158:161], v[208:211], v[32:35]
	v_mfma_f32_16x16x32_bf16 v[20:23], v[150:153], v[216:219], v[20:23]
	v_mfma_f32_16x16x32_bf16 v[16:19], v[158:161], v[216:219], v[16:19]
	v_mfma_f32_16x16x32_bf16 v[60:63], v[154:157], v[196:199], v[60:63]
	v_mfma_f32_16x16x32_bf16 v[56:59], v[170:173], v[196:199], v[56:59]
	v_mfma_f32_16x16x32_bf16 v[52:55], v[154:157], v[204:207], v[52:55]
	v_mfma_f32_16x16x32_bf16 v[48:51], v[170:173], v[204:207], v[48:51]
	v_mfma_f32_16x16x32_bf16 v[36:39], v[154:157], v[212:215], v[36:39]
	v_mfma_f32_16x16x32_bf16 v[32:35], v[170:173], v[212:215], v[32:35]
	v_mfma_f32_16x16x32_bf16 v[20:23], v[154:157], v[220:223], v[20:23]
	v_mfma_f32_16x16x32_bf16 v[16:19], v[170:173], v[220:223], v[16:19]
	s_setprio 0
	s_setprio 1
	v_mfma_f32_16x16x32_bf16 v[44:47], v[174:177], v[190:193], v[44:47]
	v_mfma_f32_16x16x32_bf16 v[40:43], v[182:185], v[190:193], v[40:43]
	v_mfma_f32_16x16x32_bf16 v[28:31], v[174:177], v[200:203], v[28:31]
	v_mfma_f32_16x16x32_bf16 v[24:27], v[182:185], v[200:203], v[24:27]
	v_mfma_f32_16x16x32_bf16 v[12:15], v[174:177], v[208:211], v[12:15]
	v_mfma_f32_16x16x32_bf16 v[8:11], v[182:185], v[208:211], v[8:11]
	v_mfma_f32_16x16x32_bf16 v[4:7], v[174:177], v[216:219], v[4:7]
	v_mfma_f32_16x16x32_bf16 v[0:3], v[182:185], v[216:219], v[0:3]
	v_mfma_f32_16x16x32_bf16 v[44:47], v[178:181], v[196:199], v[44:47]
	v_mfma_f32_16x16x32_bf16 v[40:43], v[186:189], v[196:199], v[40:43]
	v_mfma_f32_16x16x32_bf16 v[28:31], v[178:181], v[204:207], v[28:31]
	v_mfma_f32_16x16x32_bf16 v[24:27], v[186:189], v[204:207], v[24:27]
	v_mfma_f32_16x16x32_bf16 v[12:15], v[178:181], v[212:215], v[12:15]
	v_mfma_f32_16x16x32_bf16 v[8:11], v[186:189], v[212:215], v[8:11]
	v_mfma_f32_16x16x32_bf16 v[4:7], v[178:181], v[220:223], v[4:7]
	v_mfma_f32_16x16x32_bf16 v[0:3], v[186:189], v[220:223], v[0:3]
	s_barrier
	s_setprio 0
	s_add_i32 s70, 0, 0x18000
	v_add_u32_e32 v169, s70, v148
	s_add_i32 s71, 0, 0x1c000
	ds_read_b128 v[150:153], v169
	ds_read_b128 v[154:157], v169 offset:1024
	ds_read_b128 v[158:161], v169 offset:2048
	ds_read_b128 v[170:173], v169 offset:3072
	v_add_u32_e32 v169, s71, v148
	ds_read_b128 v[174:177], v169
	ds_read_b128 v[178:181], v169 offset:1024
	ds_read_b128 v[182:185], v169 offset:2048
	ds_read_b128 v[186:189], v169 offset:3072
	s_add_u32 s36, s36, 0x80000
	s_addc_u32 s37, s37, 0
	s_mov_b32 m0, s33
	v_lshl_add_u64 v[232:233], s[36:37], 0, v[134:135]
	ds_read_b128 v[190:193], v149 offset:32768
	ds_read_b128 v[196:199], v149 offset:33792
	ds_read_b128 v[200:203], v149 offset:34816
	ds_read_b128 v[204:207], v149 offset:35840
	ds_read_b128 v[208:211], v149 offset:36864
	ds_read_b128 v[212:215], v149 offset:37888
	ds_read_b128 v[216:219], v149 offset:38912
	ds_read_b128 v[220:223], v149 offset:39936
	global_load_lds_dwordx4 v[232:233], off
	v_lshl_add_u64 v[232:233], s[36:37], 0, v[136:137]
	s_mov_b32 m0, s61
	s_nop 0
	global_load_lds_dwordx4 v[232:233], off
	s_waitcnt vmcnt(8)
	s_waitcnt lgkmcnt(0)
	s_setprio 1
	s_barrier
	v_mfma_f32_16x16x32_bf16 v[124:127], v[150:153], v[190:193], v[124:127]
	v_mfma_f32_16x16x32_bf16 v[120:123], v[158:161], v[190:193], v[120:123]
	v_mfma_f32_16x16x32_bf16 v[116:119], v[150:153], v[200:203], v[116:119]
	v_mfma_f32_16x16x32_bf16 v[112:115], v[158:161], v[200:203], v[112:115]
	v_mfma_f32_16x16x32_bf16 v[100:103], v[150:153], v[208:211], v[100:103]
	v_mfma_f32_16x16x32_bf16 v[96:99], v[158:161], v[208:211], v[96:99]
	v_mfma_f32_16x16x32_bf16 v[84:87], v[150:153], v[216:219], v[84:87]
	v_mfma_f32_16x16x32_bf16 v[80:83], v[158:161], v[216:219], v[80:83]
	v_mfma_f32_16x16x32_bf16 v[124:127], v[154:157], v[196:199], v[124:127]
	v_mfma_f32_16x16x32_bf16 v[120:123], v[170:173], v[196:199], v[120:123]
	v_mfma_f32_16x16x32_bf16 v[116:119], v[154:157], v[204:207], v[116:119]
	v_mfma_f32_16x16x32_bf16 v[112:115], v[170:173], v[204:207], v[112:115]
	v_mfma_f32_16x16x32_bf16 v[100:103], v[154:157], v[212:215], v[100:103]
	v_mfma_f32_16x16x32_bf16 v[96:99], v[170:173], v[212:215], v[96:99]
	v_mfma_f32_16x16x32_bf16 v[84:87], v[154:157], v[220:223], v[84:87]
	v_mfma_f32_16x16x32_bf16 v[80:83], v[170:173], v[220:223], v[80:83]
	s_setprio 0
	s_setprio 1
	v_mfma_f32_16x16x32_bf16 v[108:111], v[174:177], v[190:193], v[108:111]
	v_mfma_f32_16x16x32_bf16 v[104:107], v[182:185], v[190:193], v[104:107]
	v_mfma_f32_16x16x32_bf16 v[92:95], v[174:177], v[200:203], v[92:95]
	v_mfma_f32_16x16x32_bf16 v[88:91], v[182:185], v[200:203], v[88:91]
	v_mfma_f32_16x16x32_bf16 v[76:79], v[174:177], v[208:211], v[76:79]
	v_mfma_f32_16x16x32_bf16 v[72:75], v[182:185], v[208:211], v[72:75]
	v_mfma_f32_16x16x32_bf16 v[68:71], v[174:177], v[216:219], v[68:71]
	v_mfma_f32_16x16x32_bf16 v[64:67], v[182:185], v[216:219], v[64:67]
	v_mfma_f32_16x16x32_bf16 v[108:111], v[178:181], v[196:199], v[108:111]
	v_mfma_f32_16x16x32_bf16 v[104:107], v[186:189], v[196:199], v[104:107]
	v_mfma_f32_16x16x32_bf16 v[92:95], v[178:181], v[204:207], v[92:95]
	v_mfma_f32_16x16x32_bf16 v[88:91], v[186:189], v[204:207], v[88:91]
	v_mfma_f32_16x16x32_bf16 v[76:79], v[178:181], v[212:215], v[76:79]
	v_mfma_f32_16x16x32_bf16 v[72:75], v[186:189], v[212:215], v[72:75]
	v_mfma_f32_16x16x32_bf16 v[68:71], v[178:181], v[220:223], v[68:71]
	v_mfma_f32_16x16x32_bf16 v[64:67], v[186:189], v[220:223], v[64:67]
	s_barrier
; #define PG8_STAGE(bufoff, gbase, voff) do { _Pragma("unroll") for (int _i = 0; _i < 2; ++_i) \
;         __builtin_amdgcn_global_load_lds((const unsigned*)((const char*)(gbase) + (voff)[_i]), (PG8_LAS unsigned*)(lds + (bufoff) + ldsw + _i * 8192), 16, 0, 0); } while (0)
; #define PG8_LDA(dst, b, h) do { _Pragma("unroll") for (int m = 0; m < 4; ++m) _Pragma("unroll") for (int k = 0; k < 2; ++k) dst[m][k] = *(const PG8_LAS bf16x8*)(lds + PG8_SA(b, h) + aoff + m * 2048 + k * 1024); } while (0)
; #define PG8_MMA(ai, bj, At, Bt) do { __builtin_amdgcn_s_setprio(1); _Pragma("unroll") for (int m = 0; m < 4; ++m) _Pragma("unroll") for (int n = 0; n < 2; ++n) _Pragma("unroll") for (int k = 0; k < 2; ++k) \
;         acc[ai][bj][m][n] = __builtin_amdgcn_mfma_f32_16x16x32_bf16(Bt[n][k], At[m][k], acc[ai][bj][m][n], 0, 0, 0); __builtin_amdgcn_s_setprio(0); } while (0)
; #define PG8_WAIT_V(n) asm volatile("s_waitcnt vmcnt(" #n ")" ::: "memory")
; #define PG8_WAIT_L(n) asm volatile("s_waitcnt lgkmcnt(" #n ")" ::: "memory")
; #define PG8_BAR __builtin_amdgcn_s_barrier()
; #define PG8_SCHED __builtin_amdgcn_sched_barrier(0)
; template <class Epi, class Sched, bool ALIGN_EPI = false, bool SP2 = false>
; __device__ __forceinline__ void gemm_phase(PG8_LAS unsigned char* lds, const Gemm g, const Sched& S, const Epi& E) {
;     ...
;             PG8_LDA(At, 1, 1); PG8_STAGE(PG8_SB(1, 0), b3, voffB); PG8_STAGE(PG8_SB(1, 1), b3 + hstepB, voffB); PG8_STAGE(PG8_SA(1, 0), a3, voffA);
;             PG8_WAIT_V(8); PG8_WAIT_L(0); PG8_BAR; PG8_MMA(1, 0, At, B0); PG8_MMA(1, 1, At, B1); PG8_BAR; PG8_SCHED;
;     ...
;     PG8_WAIT_V(0);
;     if constexpr (!ALIGN_EPI) { if (wr == 0) PG8_BAR; }
;     PG8_BAR;
	s_setprio 0
	s_add_i32 s36, s70, s2
	v_lshl_add_u64 v[224:225], v[224:225], 0, s[20:21]
	s_mov_b32 m0, s36
	ds_read_b128 v[190:193], v149 offset:49152
	ds_read_b128 v[196:199], v149 offset:50176
	ds_read_b128 v[200:203], v149 offset:51200
	ds_read_b128 v[204:207], v149 offset:52224
	ds_read_b128 v[208:211], v149 offset:53248
	ds_read_b128 v[212:215], v149 offset:54272
	ds_read_b128 v[216:219], v149 offset:55296
	ds_read_b128 v[220:223], v149 offset:56320
	global_load_lds_dwordx4 v[224:225], off
	s_add_i32 m0, s36, 0x2000
	s_add_u32 s34, s34, 0x80080
	v_lshl_add_u64 v[224:225], v[226:227], 0, s[20:21]
	s_addc_u32 s35, s35, 0
	s_add_i32 s36, s71, s2
	global_load_lds_dwordx4 v[224:225], off
	v_lshl_add_u64 v[224:225], s[34:35], 0, v[132:133]
	s_mov_b32 m0, s36
	s_nop 0
	global_load_lds_dwordx4 v[224:225], off
	v_lshl_add_u64 v[224:225], s[34:35], 0, v[138:139]
	s_add_i32 m0, s36, 0x2000
	s_nop 0
	global_load_lds_dwordx4 v[224:225], off
	v_lshl_add_u64 v[224:225], v[228:229], 0, s[20:21]
	s_mov_b32 m0, s63
	s_nop 0
	global_load_lds_dwordx4 v[224:225], off
	v_lshl_add_u64 v[224:225], v[230:231], 0, s[20:21]
	s_mov_b32 m0, s64
	s_nop 0
	global_load_lds_dwordx4 v[224:225], off
	s_waitcnt vmcnt(8)
	s_waitcnt lgkmcnt(0)
	s_setprio 1
	s_barrier
	v_mfma_f32_16x16x32_bf16 v[60:63], v[150:153], v[190:193], v[60:63]
	v_mfma_f32_16x16x32_bf16 v[56:59], v[158:161], v[190:193], v[56:59]
	v_mfma_f32_16x16x32_bf16 v[52:55], v[150:153], v[200:203], v[52:55]
	v_mfma_f32_16x16x32_bf16 v[48:51], v[158:161], v[200:203], v[48:51]
	v_mfma_f32_16x16x32_bf16 v[36:39], v[150:153], v[208:211], v[36:39]
	v_mfma_f32_16x16x32_bf16 v[32:35], v[158:161], v[208:211], v[32:35]
	v_mfma_f32_16x16x32_bf16 v[20:23], v[150:153], v[216:219], v[20:23]
	v_mfma_f32_16x16x32_bf16 v[16:19], v[158:161], v[216:219], v[16:19]
	v_mfma_f32_16x16x32_bf16 v[60:63], v[154:157], v[196:199], v[60:63]
	v_mfma_f32_16x16x32_bf16 v[56:59], v[170:173], v[196:199], v[56:59]
	v_mfma_f32_16x16x32_bf16 v[52:55], v[154:157], v[204:207], v[52:55]
	v_mfma_f32_16x16x32_bf16 v[48:51], v[170:173], v[204:207], v[48:51]
	v_mfma_f32_16x16x32_bf16 v[36:39], v[154:157], v[212:215], v[36:39]
	v_mfma_f32_16x16x32_bf16 v[32:35], v[170:173], v[212:215], v[32:35]
	v_mfma_f32_16x16x32_bf16 v[20:23], v[154:157], v[220:223], v[20:23]
	v_mfma_f32_16x16x32_bf16 v[16:19], v[170:173], v[220:223], v[16:19]
	s_setprio 0
	s_setprio 1
	v_mfma_f32_16x16x32_bf16 v[44:47], v[174:177], v[190:193], v[44:47]
	v_mfma_f32_16x16x32_bf16 v[40:43], v[182:185], v[190:193], v[40:43]
	v_mfma_f32_16x16x32_bf16 v[28:31], v[174:177], v[200:203], v[28:31]
	v_mfma_f32_16x16x32_bf16 v[24:27], v[182:185], v[200:203], v[24:27]
	v_mfma_f32_16x16x32_bf16 v[12:15], v[174:177], v[208:211], v[12:15]
	v_mfma_f32_16x16x32_bf16 v[8:11], v[182:185], v[208:211], v[8:11]
	v_mfma_f32_16x16x32_bf16 v[4:7], v[174:177], v[216:219], v[4:7]
	v_mfma_f32_16x16x32_bf16 v[0:3], v[182:185], v[216:219], v[0:3]
	v_mfma_f32_16x16x32_bf16 v[44:47], v[178:181], v[196:199], v[44:47]
	v_mfma_f32_16x16x32_bf16 v[40:43], v[186:189], v[196:199], v[40:43]
	v_mfma_f32_16x16x32_bf16 v[28:31], v[178:181], v[204:207], v[28:31]
	v_mfma_f32_16x16x32_bf16 v[24:27], v[186:189], v[204:207], v[24:27]
	v_mfma_f32_16x16x32_bf16 v[12:15], v[178:181], v[212:215], v[12:15]
	v_mfma_f32_16x16x32_bf16 v[8:11], v[186:189], v[212:215], v[8:11]
	v_mfma_f32_16x16x32_bf16 v[4:7], v[178:181], v[220:223], v[4:7]
	v_mfma_f32_16x16x32_bf16 v[0:3], v[186:189], v[220:223], v[0:3]
	s_barrier
	s_setprio 0
	s_add_i32 s69, s69, 2
	s_add_u32 s30, s30, 0x100
	s_addc_u32 s31, s31, 0
	s_cmp_lt_u32 s69, 30
	s_cbranch_scc1 .LBB0_736
	s_waitcnt vmcnt(0)
	s_cmpk_gt_u32 s0, 0xff
	s_cbranch_scc1 .LBB0_739
	s_barrier

; #define PG8_STAGE(bufoff, gbase, voff) do { _Pragma("unroll") for (int _i = 0; _i < 2; ++_i) \
;         __builtin_amdgcn_global_load_lds((const unsigned*)((const char*)(gbase) + (voff)[_i]), (PG8_LAS unsigned*)(lds + (bufoff) + ldsw + _i * 8192), 16, 0, 0); } while (0)
; #define PG8_LDA(dst, b, h) do { _Pragma("unroll") for (int m = 0; m < 4; ++m) _Pragma("unroll") for (int k = 0; k < 2; ++k) dst[m][k] = *(const PG8_LAS bf16x8*)(lds + PG8_SA(b, h) + aoff + m * 2048 + k * 1024); } while (0)
; #define PG8_LDB(dst, b, h) do { _Pragma("unroll") for (int n = 0; n < 2; ++n) _Pragma("unroll") for (int k = 0; k < 2; ++k) dst[n][k] = *(const PG8_LAS bf16x8*)(lds + PG8_SB(b, h) + boff + n * 2048 + k * 1024); } while (0)
; #define PG8_MMA(ai, bj, At, Bt) do { __builtin_amdgcn_s_setprio(1); _Pragma("unroll") for (int m = 0; m < 4; ++m) _Pragma("unroll") for (int n = 0; n < 2; ++n) _Pragma("unroll") for (int k = 0; k < 2; ++k) \
;         acc[ai][bj][m][n] = __builtin_amdgcn_mfma_f32_16x16x32_bf16(Bt[n][k], At[m][k], acc[ai][bj][m][n], 0, 0, 0); __builtin_amdgcn_s_setprio(0); } while (0)
; #define PG8_WAIT_V(n) asm volatile("s_waitcnt vmcnt(" #n ")" ::: "memory")
; #define PG8_WAIT_L(n) asm volatile("s_waitcnt lgkmcnt(" #n ")" ::: "memory")
; #define PG8_BAR __builtin_amdgcn_s_barrier()
; #define PG8_SCHED __builtin_amdgcn_sched_barrier(0)
; template <class Epi, class Sched, bool ALIGN_EPI = false, bool SP2 = false>
; __device__ __forceinline__ void gemm_phase(PG8_LAS unsigned char* lds, const Gemm g, const Sched& S, const Epi& E) {
;     ...
;             PG8_LDB(B0, 0, 0); PG8_LDB(B1, 0, 1); PG8_SCHED; PG8_LDA(At, 0, 0); PG8_STAGE(PG8_SA(1, 1), a1 + hstepA, voffA);
;             PG8_WAIT_V(8); PG8_WAIT_L(0); PG8_BAR; PG8_MMA(0, 0, At, B0); PG8_MMA(0, 1, At, B1); PG8_BAR; PG8_SCHED;
;             PG8_LDA(At, 0, 1); PG8_STAGE(PG8_SB(0, 0), b2, voffB); PG8_STAGE(PG8_SB(0, 1), b2 + hstepB, voffB); PG8_STAGE(PG8_SA(0, 0), a2, voffA);
;             PG8_WAIT_V(8); PG8_WAIT_L(0); PG8_BAR; PG8_MMA(1, 0, At, B0); PG8_MMA(1, 1, At, B1); PG8_BAR; PG8_SCHED;
.LBB0_894:
	ds_read_b128 v[64:67], v172
	ds_read_b128 v[108:111], v172 offset:1024
	ds_read_b128 v[116:119], v172 offset:2048
	ds_read_b128 v[128:131], v172 offset:3072
	ds_read_b128 v[156:159], v173
	ds_read_b128 v[176:179], v173 offset:1024
	ds_read_b128 v[180:183], v173 offset:2048
	ds_read_b128 v[184:187], v173 offset:3072
	s_add_u32 s28, s26, 0x100
	s_addc_u32 s29, s27, 0
	s_cmpk_eq_i32 s57, 0x54
	s_cselect_b32 s35, s7, s29
	s_cselect_b32 s34, s6, s28
	s_cselect_b32 s31, s25, s55
	s_cselect_b32 s30, s24, s54
	v_lshl_add_u64 v[160:161], s[26:27], 0, v[148:149]
	s_add_i32 m0, s36, 0xc000
	ds_read_b128 v[188:191], v174
	ds_read_b128 v[196:199], v174 offset:1024
	ds_read_b128 v[200:203], v174 offset:2048
	ds_read_b128 v[204:207], v174 offset:3072
	ds_read_b128 v[208:211], v174 offset:4096
	ds_read_b128 v[212:215], v174 offset:5120
	ds_read_b128 v[216:219], v174 offset:6144
	ds_read_b128 v[220:223], v174 offset:7168
	global_load_lds_dwordx4 v[160:161], off
	v_lshl_add_u64 v[160:161], s[26:27], 0, v[150:151]
	s_add_i32 m0, s36, 0xe000
	s_nop 0
	global_load_lds_dwordx4 v[160:161], off
	s_waitcnt vmcnt(8)
	s_waitcnt lgkmcnt(0)
	s_setprio 1
	s_barrier
	v_mfma_f32_16x16x32_bf16 v[140:143], v[64:67], v[188:191], v[140:143]
	v_mfma_f32_16x16x32_bf16 v[136:139], v[116:119], v[188:191], v[136:139]
	v_mfma_f32_16x16x32_bf16 v[120:123], v[64:67], v[200:203], v[120:123]
	v_mfma_f32_16x16x32_bf16 v[112:115], v[116:119], v[200:203], v[112:115]
	v_mfma_f32_16x16x32_bf16 v[96:99], v[64:67], v[208:211], v[96:99]
	v_mfma_f32_16x16x32_bf16 v[92:95], v[116:119], v[208:211], v[92:95]
	v_mfma_f32_16x16x32_bf16 v[80:83], v[64:67], v[216:219], v[80:83]
	v_mfma_f32_16x16x32_bf16 v[76:79], v[116:119], v[216:219], v[76:79]
	v_mfma_f32_16x16x32_bf16 v[140:143], v[108:111], v[196:199], v[140:143]
	v_mfma_f32_16x16x32_bf16 v[136:139], v[128:131], v[196:199], v[136:139]
	v_mfma_f32_16x16x32_bf16 v[120:123], v[108:111], v[204:207], v[120:123]
	v_mfma_f32_16x16x32_bf16 v[112:115], v[128:131], v[204:207], v[112:115]
	v_mfma_f32_16x16x32_bf16 v[96:99], v[108:111], v[212:215], v[96:99]
	v_mfma_f32_16x16x32_bf16 v[92:95], v[128:131], v[212:215], v[92:95]
	v_mfma_f32_16x16x32_bf16 v[80:83], v[108:111], v[220:223], v[80:83]
	v_mfma_f32_16x16x32_bf16 v[76:79], v[128:131], v[220:223], v[76:79]
	s_setprio 0
	s_setprio 1
	v_mfma_f32_16x16x32_bf16 v[132:135], v[156:159], v[188:191], v[132:135]
	v_mfma_f32_16x16x32_bf16 v[124:127], v[180:183], v[188:191], v[124:127]
	v_mfma_f32_16x16x32_bf16 v[104:107], v[156:159], v[200:203], v[104:107]
	v_mfma_f32_16x16x32_bf16 v[100:103], v[180:183], v[200:203], v[100:103]
	v_mfma_f32_16x16x32_bf16 v[88:91], v[156:159], v[208:211], v[88:91]
	v_mfma_f32_16x16x32_bf16 v[84:87], v[180:183], v[208:211], v[84:87]
	v_mfma_f32_16x16x32_bf16 v[72:75], v[156:159], v[216:219], v[72:75]
	v_mfma_f32_16x16x32_bf16 v[68:71], v[180:183], v[216:219], v[68:71]
	v_mfma_f32_16x16x32_bf16 v[132:135], v[176:179], v[196:199], v[132:135]
	v_mfma_f32_16x16x32_bf16 v[124:127], v[184:187], v[196:199], v[124:127]
	v_mfma_f32_16x16x32_bf16 v[104:107], v[176:179], v[204:207], v[104:107]
	v_mfma_f32_16x16x32_bf16 v[100:103], v[184:187], v[204:207], v[100:103]
	v_mfma_f32_16x16x32_bf16 v[88:91], v[176:179], v[212:215], v[88:91]
	v_mfma_f32_16x16x32_bf16 v[84:87], v[184:187], v[212:215], v[84:87]
	v_mfma_f32_16x16x32_bf16 v[72:75], v[176:179], v[220:223], v[72:75]
	v_mfma_f32_16x16x32_bf16 v[68:71], v[184:187], v[220:223], v[68:71]
	s_barrier
	s_setprio 0
	s_add_i32 s26, s56, s33
	v_lshl_add_u64 v[160:161], s[30:31], 0, v[146:147]
	s_mov_b32 m0, s26
	ds_read_b128 v[188:191], v174 offset:16384
	ds_read_b128 v[196:199], v174 offset:17408
	ds_read_b128 v[200:203], v174 offset:18432
	ds_read_b128 v[204:207], v174 offset:19456
	ds_read_b128 v[208:211], v174 offset:20480
	ds_read_b128 v[212:215], v174 offset:21504
	ds_read_b128 v[216:219], v174 offset:22528
	ds_read_b128 v[220:223], v174 offset:23552
	global_load_lds_dwordx4 v[160:161], off
	s_add_i32 m0, s26, 0x2000
	s_add_u32 s26, s30, 0x160000
	v_lshl_add_u64 v[192:193], s[30:31], 0, v[144:145]
	s_addc_u32 s27, s31, 0
	s_add_i32 s58, s45, s33
	global_load_lds_dwordx4 v[192:193], off
	v_lshl_add_u64 v[224:225], s[26:27], 0, v[146:147]
	s_mov_b32 m0, s58
	v_lshl_add_u64 v[226:227], s[34:35], 0, v[144:145]
	global_load_lds_dwordx4 v[224:225], off
	v_lshl_add_u64 v[224:225], s[26:27], 0, v[144:145]
	s_add_i32 m0, s58, 0x2000
	s_nop 0
	global_load_lds_dwordx4 v[224:225], off
	v_lshl_add_u64 v[224:225], s[34:35], 0, v[146:147]
	s_mov_b32 m0, s36
	s_nop 0
	global_load_lds_dwordx4 v[224:225], off
	s_mov_b32 m0, s37
	s_nop 0
	global_load_lds_dwordx4 v[226:227], off
	s_waitcnt vmcnt(8)
	s_waitcnt lgkmcnt(0)
	s_setprio 1
	s_barrier
; #define PG8_STAGE(bufoff, gbase, voff) do { _Pragma("unroll") for (int _i = 0; _i < 2; ++_i) \
;         __builtin_amdgcn_global_load_lds((const unsigned*)((const char*)(gbase) + (voff)[_i]), (PG8_LAS unsigned*)(lds + (bufoff) + ldsw + _i * 8192), 16, 0, 0); } while (0)
; #define PG8_LDA(dst, b, h) do { _Pragma("unroll") for (int m = 0; m < 4; ++m) _Pragma("unroll") for (int k = 0; k < 2; ++k) dst[m][k] = *(const PG8_LAS bf16x8*)(lds + PG8_SA(b, h) + aoff + m * 2048 + k * 1024); } while (0)
; #define PG8_LDB(dst, b, h) do { _Pragma("unroll") for (int n = 0; n < 2; ++n) _Pragma("unroll") for (int k = 0; k < 2; ++k) dst[n][k] = *(const PG8_LAS bf16x8*)(lds + PG8_SB(b, h) + boff + n * 2048 + k * 1024); } while (0)
; #define PG8_MMA(ai, bj, At, Bt) do { __builtin_amdgcn_s_setprio(1); _Pragma("unroll") for (int m = 0; m < 4; ++m) _Pragma("unroll") for (int n = 0; n < 2; ++n) _Pragma("unroll") for (int k = 0; k < 2; ++k) \
;         acc[ai][bj][m][n] = __builtin_amdgcn_mfma_f32_16x16x32_bf16(Bt[n][k], At[m][k], acc[ai][bj][m][n], 0, 0, 0); __builtin_amdgcn_s_setprio(0); } while (0)
; #define PG8_WAIT_V(n) asm volatile("s_waitcnt vmcnt(" #n ")" ::: "memory")
; #define PG8_WAIT_L(n) asm volatile("s_waitcnt lgkmcnt(" #n ")" ::: "memory")
; #define PG8_BAR __builtin_amdgcn_s_barrier()
; #define PG8_SCHED __builtin_amdgcn_sched_barrier(0)
; template <class Epi, class Sched, bool ALIGN_EPI = false, bool SP2 = false>
; __device__ __forceinline__ void gemm_phase(PG8_LAS unsigned char* lds, const Gemm g, const Sched& S, const Epi& E) {
;     ...
;             PG8_WAIT_V(8); PG8_WAIT_L(0); PG8_BAR; PG8_MMA(1, 0, At, B0); PG8_MMA(1, 1, At, B1); PG8_BAR; PG8_SCHED;
;             PG8_LDB(B0, 1, 0); PG8_LDB(B1, 1, 1); PG8_SCHED; PG8_LDA(At, 1, 0); PG8_STAGE(PG8_SA(0, 1), a2 + hstepA, voffA);
;             PG8_WAIT_V(8); PG8_WAIT_L(0); PG8_BAR; PG8_MMA(0, 0, At, B0); PG8_MMA(0, 1, At, B1); PG8_BAR; PG8_SCHED;
	v_mfma_f32_16x16x32_bf16 v[60:63], v[64:67], v[188:191], v[60:63]
	v_mfma_f32_16x16x32_bf16 v[56:59], v[116:119], v[188:191], v[56:59]
	v_mfma_f32_16x16x32_bf16 v[44:47], v[64:67], v[200:203], v[44:47]
	v_mfma_f32_16x16x32_bf16 v[40:43], v[116:119], v[200:203], v[40:43]
	v_mfma_f32_16x16x32_bf16 v[28:31], v[64:67], v[208:211], v[28:31]
	v_mfma_f32_16x16x32_bf16 v[24:27], v[116:119], v[208:211], v[24:27]
	v_mfma_f32_16x16x32_bf16 v[12:15], v[64:67], v[216:219], v[12:15]
	v_mfma_f32_16x16x32_bf16 v[8:11], v[116:119], v[216:219], v[8:11]
	v_mfma_f32_16x16x32_bf16 v[60:63], v[108:111], v[196:199], v[60:63]
	v_mfma_f32_16x16x32_bf16 v[56:59], v[128:131], v[196:199], v[56:59]
	v_mfma_f32_16x16x32_bf16 v[44:47], v[108:111], v[204:207], v[44:47]
	v_mfma_f32_16x16x32_bf16 v[40:43], v[128:131], v[204:207], v[40:43]
	v_mfma_f32_16x16x32_bf16 v[28:31], v[108:111], v[212:215], v[28:31]
	v_mfma_f32_16x16x32_bf16 v[24:27], v[128:131], v[212:215], v[24:27]
	v_mfma_f32_16x16x32_bf16 v[12:15], v[108:111], v[220:223], v[12:15]
	v_mfma_f32_16x16x32_bf16 v[8:11], v[128:131], v[220:223], v[8:11]
	s_setprio 0
	s_setprio 1
	v_mfma_f32_16x16x32_bf16 v[52:55], v[156:159], v[188:191], v[52:55]
	v_mfma_f32_16x16x32_bf16 v[48:51], v[180:183], v[188:191], v[48:51]
	v_mfma_f32_16x16x32_bf16 v[36:39], v[156:159], v[200:203], v[36:39]
	v_mfma_f32_16x16x32_bf16 v[32:35], v[180:183], v[200:203], v[32:35]
	v_mfma_f32_16x16x32_bf16 v[20:23], v[156:159], v[208:211], v[20:23]
	v_mfma_f32_16x16x32_bf16 v[16:19], v[180:183], v[208:211], v[16:19]
	v_mfma_f32_16x16x32_bf16 v[4:7], v[156:159], v[216:219], v[4:7]
	v_mfma_f32_16x16x32_bf16 v[0:3], v[180:183], v[216:219], v[0:3]
	v_mfma_f32_16x16x32_bf16 v[52:55], v[176:179], v[196:199], v[52:55]
	v_mfma_f32_16x16x32_bf16 v[48:51], v[184:187], v[196:199], v[48:51]
	v_mfma_f32_16x16x32_bf16 v[36:39], v[176:179], v[204:207], v[36:39]
	v_mfma_f32_16x16x32_bf16 v[32:35], v[184:187], v[204:207], v[32:35]
	v_mfma_f32_16x16x32_bf16 v[20:23], v[176:179], v[212:215], v[20:23]
	v_mfma_f32_16x16x32_bf16 v[16:19], v[184:187], v[212:215], v[16:19]
	v_mfma_f32_16x16x32_bf16 v[4:7], v[176:179], v[220:223], v[4:7]
	v_mfma_f32_16x16x32_bf16 v[0:3], v[184:187], v[220:223], v[0:3]
	s_barrier
	s_setprio 0
	s_add_i32 s58, 0, 0x18000
	s_add_i32 s59, 0, 0x1c000
	v_add_u32_e32 v128, s58, v170
	v_add_u32_e32 v175, s59, v170
	ds_read_b128 v[64:67], v128
	ds_read_b128 v[108:111], v128 offset:1024
	ds_read_b128 v[116:119], v128 offset:2048
	ds_read_b128 v[128:131], v128 offset:3072
	ds_read_b128 v[156:159], v175
	ds_read_b128 v[176:179], v175 offset:1024
	ds_read_b128 v[180:183], v175 offset:2048
	ds_read_b128 v[184:187], v175 offset:3072
	s_add_u32 s26, s34, 0x160000
	s_addc_u32 s27, s35, 0
	s_mov_b32 m0, s38
	v_lshl_add_u64 v[228:229], s[26:27], 0, v[146:147]
	ds_read_b128 v[188:191], v174 offset:32768
	ds_read_b128 v[196:199], v174 offset:33792
	ds_read_b128 v[200:203], v174 offset:34816
	ds_read_b128 v[204:207], v174 offset:35840
	ds_read_b128 v[208:211], v174 offset:36864
	ds_read_b128 v[212:215], v174 offset:37888
	ds_read_b128 v[216:219], v174 offset:38912
	ds_read_b128 v[220:223], v174 offset:39936
	global_load_lds_dwordx4 v[228:229], off
	v_lshl_add_u64 v[228:229], s[26:27], 0, v[144:145]
	s_mov_b32 m0, s39
	s_nop 0
	global_load_lds_dwordx4 v[228:229], off
	s_waitcnt vmcnt(8)
	s_waitcnt lgkmcnt(0)
	s_setprio 1
	s_barrier
	v_mfma_f32_16x16x32_bf16 v[140:143], v[64:67], v[188:191], v[140:143]
	v_mfma_f32_16x16x32_bf16 v[136:139], v[116:119], v[188:191], v[136:139]
	v_mfma_f32_16x16x32_bf16 v[120:123], v[64:67], v[200:203], v[120:123]
	v_mfma_f32_16x16x32_bf16 v[112:115], v[116:119], v[200:203], v[112:115]
	v_mfma_f32_16x16x32_bf16 v[96:99], v[64:67], v[208:211], v[96:99]
	v_mfma_f32_16x16x32_bf16 v[92:95], v[116:119], v[208:211], v[92:95]
	v_mfma_f32_16x16x32_bf16 v[80:83], v[64:67], v[216:219], v[80:83]
	v_mfma_f32_16x16x32_bf16 v[76:79], v[116:119], v[216:219], v[76:79]
	v_mfma_f32_16x16x32_bf16 v[140:143], v[108:111], v[196:199], v[140:143]
	v_mfma_f32_16x16x32_bf16 v[136:139], v[128:131], v[196:199], v[136:139]
	v_mfma_f32_16x16x32_bf16 v[120:123], v[108:111], v[204:207], v[120:123]
	v_mfma_f32_16x16x32_bf16 v[112:115], v[128:131], v[204:207], v[112:115]
	v_mfma_f32_16x16x32_bf16 v[96:99], v[108:111], v[212:215], v[96:99]
	v_mfma_f32_16x16x32_bf16 v[92:95], v[128:131], v[212:215], v[92:95]
	v_mfma_f32_16x16x32_bf16 v[80:83], v[108:111], v[220:223], v[80:83]
	v_mfma_f32_16x16x32_bf16 v[76:79], v[128:131], v[220:223], v[76:79]
	s_setprio 0
	s_setprio 1
	v_mfma_f32_16x16x32_bf16 v[132:135], v[156:159], v[188:191], v[132:135]
	v_mfma_f32_16x16x32_bf16 v[124:127], v[180:183], v[188:191], v[124:127]
	v_mfma_f32_16x16x32_bf16 v[104:107], v[156:159], v[200:203], v[104:107]
	v_mfma_f32_16x16x32_bf16 v[100:103], v[180:183], v[200:203], v[100:103]
	v_mfma_f32_16x16x32_bf16 v[88:91], v[156:159], v[208:211], v[88:91]
	v_mfma_f32_16x16x32_bf16 v[84:87], v[180:183], v[208:211], v[84:87]
	v_mfma_f32_16x16x32_bf16 v[72:75], v[156:159], v[216:219], v[72:75]
	v_mfma_f32_16x16x32_bf16 v[68:71], v[180:183], v[216:219], v[68:71]
	v_mfma_f32_16x16x32_bf16 v[132:135], v[176:179], v[196:199], v[132:135]
	v_mfma_f32_16x16x32_bf16 v[124:127], v[184:187], v[196:199], v[124:127]
	v_mfma_f32_16x16x32_bf16 v[104:107], v[176:179], v[204:207], v[104:107]
	v_mfma_f32_16x16x32_bf16 v[100:103], v[184:187], v[204:207], v[100:103]
	v_mfma_f32_16x16x32_bf16 v[88:91], v[176:179], v[212:215], v[88:91]
	v_mfma_f32_16x16x32_bf16 v[84:87], v[184:187], v[212:215], v[84:87]
	v_mfma_f32_16x16x32_bf16 v[72:75], v[176:179], v[220:223], v[72:75]
	v_mfma_f32_16x16x32_bf16 v[68:71], v[184:187], v[220:223], v[68:71]
	s_barrier
; #define PG8_STAGE(bufoff, gbase, voff) do { _Pragma("unroll") for (int _i = 0; _i < 2; ++_i) \
;         __builtin_amdgcn_global_load_lds((const unsigned*)((const char*)(gbase) + (voff)[_i]), (PG8_LAS unsigned*)(lds + (bufoff) + ldsw + _i * 8192), 16, 0, 0); } while (0)
; #define PG8_LDA(dst, b, h) do { _Pragma("unroll") for (int m = 0; m < 4; ++m) _Pragma("unroll") for (int k = 0; k < 2; ++k) dst[m][k] = *(const PG8_LAS bf16x8*)(lds + PG8_SA(b, h) + aoff + m * 2048 + k * 1024); } while (0)
; #define PG8_MMA(ai, bj, At, Bt) do { __builtin_amdgcn_s_setprio(1); _Pragma("unroll") for (int m = 0; m < 4; ++m) _Pragma("unroll") for (int n = 0; n < 2; ++n) _Pragma("unroll") for (int k = 0; k < 2; ++k) \
;         acc[ai][bj][m][n] = __builtin_amdgcn_mfma_f32_16x16x32_bf16(Bt[n][k], At[m][k], acc[ai][bj][m][n], 0, 0, 0); __builtin_amdgcn_s_setprio(0); } while (0)
; #define PG8_WAIT_V(n) asm volatile("s_waitcnt vmcnt(" #n ")" ::: "memory")
; #define PG8_WAIT_L(n) asm volatile("s_waitcnt lgkmcnt(" #n ")" ::: "memory")
; #define PG8_BAR __builtin_amdgcn_s_barrier()
; #define PG8_SCHED __builtin_amdgcn_sched_barrier(0)
; template <class Epi, class Sched, bool ALIGN_EPI = false, bool SP2 = false>
; __device__ __forceinline__ void gemm_phase(PG8_LAS unsigned char* lds, const Gemm g, const Sched& S, const Epi& E) {
;     ...
;             PG8_LDA(At, 1, 1); PG8_STAGE(PG8_SB(1, 0), b3, voffB); PG8_STAGE(PG8_SB(1, 1), b3 + hstepB, voffB); PG8_STAGE(PG8_SA(1, 0), a3, voffA);
;             PG8_WAIT_V(8); PG8_WAIT_L(0); PG8_BAR; PG8_MMA(1, 0, At, B0); PG8_MMA(1, 1, At, B1); PG8_BAR; PG8_SCHED;
;     ...
;         if constexpr (ALIGN_EPI) { if (wr == 0) PG8_BAR; }
	s_setprio 0
	s_add_i32 s26, s58, s33
	v_lshl_add_u64 v[160:161], v[160:161], 0, s[10:11]
	s_mov_b32 m0, s26
	ds_read_b128 v[188:191], v174 offset:49152
	ds_read_b128 v[196:199], v174 offset:50176
	ds_read_b128 v[200:203], v174 offset:51200
	ds_read_b128 v[204:207], v174 offset:52224
	ds_read_b128 v[208:211], v174 offset:53248
	ds_read_b128 v[212:215], v174 offset:54272
	ds_read_b128 v[216:219], v174 offset:55296
	ds_read_b128 v[220:223], v174 offset:56320
	global_load_lds_dwordx4 v[160:161], off
	s_add_i32 m0, s26, 0x2000
	s_add_u32 s26, s30, 0x160080
	v_lshl_add_u64 v[160:161], v[192:193], 0, s[10:11]
	s_addc_u32 s27, s31, 0
	s_add_i32 s30, s59, s33
	global_load_lds_dwordx4 v[160:161], off
	v_lshl_add_u64 v[160:161], s[26:27], 0, v[146:147]
	s_mov_b32 m0, s30
	s_nop 0
	global_load_lds_dwordx4 v[160:161], off
	v_lshl_add_u64 v[160:161], s[26:27], 0, v[144:145]
	s_add_i32 m0, s30, 0x2000
	s_nop 0
	global_load_lds_dwordx4 v[160:161], off
	v_lshl_add_u64 v[160:161], v[224:225], 0, s[10:11]
	s_mov_b32 m0, s43
	s_nop 0
	global_load_lds_dwordx4 v[160:161], off
	v_lshl_add_u64 v[160:161], v[226:227], 0, s[10:11]
	s_mov_b32 m0, s44
	s_nop 0
	global_load_lds_dwordx4 v[160:161], off
	s_waitcnt vmcnt(8)
	s_waitcnt lgkmcnt(0)
	s_setprio 1
	s_barrier
	v_mfma_f32_16x16x32_bf16 v[60:63], v[64:67], v[188:191], v[60:63]
	v_mfma_f32_16x16x32_bf16 v[56:59], v[116:119], v[188:191], v[56:59]
	v_mfma_f32_16x16x32_bf16 v[44:47], v[64:67], v[200:203], v[44:47]
	v_mfma_f32_16x16x32_bf16 v[40:43], v[116:119], v[200:203], v[40:43]
	v_mfma_f32_16x16x32_bf16 v[28:31], v[64:67], v[208:211], v[28:31]
	v_mfma_f32_16x16x32_bf16 v[24:27], v[116:119], v[208:211], v[24:27]
	v_mfma_f32_16x16x32_bf16 v[12:15], v[64:67], v[216:219], v[12:15]
	v_mfma_f32_16x16x32_bf16 v[8:11], v[116:119], v[216:219], v[8:11]
	v_mfma_f32_16x16x32_bf16 v[60:63], v[108:111], v[196:199], v[60:63]
	v_mfma_f32_16x16x32_bf16 v[56:59], v[128:131], v[196:199], v[56:59]
	v_mfma_f32_16x16x32_bf16 v[44:47], v[108:111], v[204:207], v[44:47]
	v_mfma_f32_16x16x32_bf16 v[40:43], v[128:131], v[204:207], v[40:43]
	v_mfma_f32_16x16x32_bf16 v[28:31], v[108:111], v[212:215], v[28:31]
	v_mfma_f32_16x16x32_bf16 v[24:27], v[128:131], v[212:215], v[24:27]
	v_mfma_f32_16x16x32_bf16 v[12:15], v[108:111], v[220:223], v[12:15]
	v_mfma_f32_16x16x32_bf16 v[8:11], v[128:131], v[220:223], v[8:11]
	s_setprio 0
	s_setprio 1
	v_mfma_f32_16x16x32_bf16 v[52:55], v[156:159], v[188:191], v[52:55]
	v_mfma_f32_16x16x32_bf16 v[48:51], v[180:183], v[188:191], v[48:51]
	v_mfma_f32_16x16x32_bf16 v[36:39], v[156:159], v[200:203], v[36:39]
	v_mfma_f32_16x16x32_bf16 v[32:35], v[180:183], v[200:203], v[32:35]
	v_mfma_f32_16x16x32_bf16 v[20:23], v[156:159], v[208:211], v[20:23]
	v_mfma_f32_16x16x32_bf16 v[16:19], v[180:183], v[208:211], v[16:19]
	v_mfma_f32_16x16x32_bf16 v[4:7], v[156:159], v[216:219], v[4:7]
	v_mfma_f32_16x16x32_bf16 v[0:3], v[180:183], v[216:219], v[0:3]
	v_mfma_f32_16x16x32_bf16 v[52:55], v[176:179], v[196:199], v[52:55]
	v_mfma_f32_16x16x32_bf16 v[48:51], v[184:187], v[196:199], v[48:51]
	v_mfma_f32_16x16x32_bf16 v[36:39], v[176:179], v[204:207], v[36:39]
	v_mfma_f32_16x16x32_bf16 v[32:35], v[184:187], v[204:207], v[32:35]
	v_mfma_f32_16x16x32_bf16 v[20:23], v[176:179], v[212:215], v[20:23]
	v_mfma_f32_16x16x32_bf16 v[16:19], v[184:187], v[212:215], v[16:19]
	v_mfma_f32_16x16x32_bf16 v[4:7], v[176:179], v[220:223], v[4:7]
	v_mfma_f32_16x16x32_bf16 v[0:3], v[184:187], v[220:223], v[0:3]
	s_barrier
	s_setprio 0
	s_add_i32 s57, s57, 2
	s_add_u32 s54, s54, 0x100
	s_addc_u32 s55, s55, 0
	s_cmpk_gt_u32 s57, 0x55
	s_mov_b64 s[26:27], s[28:29]
	s_cbranch_scc0 .LBB0_894
	s_and_b64 vcc, exec, s[16:17]
	s_cbranch_vccz .LBB0_897
	s_barrier
